# attention softmax VALU spread evenly over PV MFMA gaps (<=7 issue units per gap); prenorm row loads batched (8 per row)
# speedup vs baseline: 1.0328x; 1.0025x over previous
; template <int SRC> __device__ __forceinline__ void prenorm_rows(const LArgs& a, int nrows, const float* nw, const float* mods_layer, int shift_part, bf16* dst) {
;     ...
;         for (int r = 0; r < 16; ++r) {
;             const float* src = src0 + (size_t)r * DM; f32x4 v[8]; float ss = 0.f;
; #pragma unroll
;             for (int j = 0; j < 8; ++j) { v[j] = *(const f32x4*)(src + 4 * lane + 256 * j); ss += (v[j].x * v[j].x + v[j].y * v[j].y) + (v[j].z * v[j].z + v[j].w * v[j].w); }
;             const float rn = 1.f / sqrtf(wave_sum(ss) * (1.f / DM) + 1e-6f);
.LBB0_234:
	v_lshl_add_u64 v[136:137], v[100:101], 0, s[8:9]
	v_add_co_u32_e32 v32, vcc, 0xd000000, v136
	v_ashrrev_i32_e32 v135, 31, v134
	s_nop 0
	v_addc_co_u32_e32 v33, vcc, 0, v137, vcc
	v_lshlrev_b64 v[142:143], 12, v[134:135]
	s_add_u32 s8, s8, 0x4000
	s_addc_u32 s9, s9, 0
	s_cmp_eq_u32 s8, 0x20000
	s_nop 1
	v_add_co_u32_e32 v138, vcc, s63, v136
	s_nop 1
	s_nop 0
	v_addc_co_u32_e32 v139, vcc, 0, v137, vcc
	v_add_co_u32_e32 v152, vcc, s60, v136
	s_nop 1
	v_addc_co_u32_e32 v153, vcc, 0, v137, vcc
	global_load_dwordx4 v[60:63], v[32:33], off
	global_load_dwordx4 v[56:59], v[32:33], off offset:1024
	global_load_dwordx4 v[52:55], v[32:33], off offset:2048
	global_load_dwordx4 v[48:51], v[32:33], off offset:3072
	global_load_dwordx4 v[44:47], v[152:153], off
	global_load_dwordx4 v[40:43], v[152:153], off offset:1024
	global_load_dwordx4 v[36:39], v[152:153], off offset:2048
	global_load_dwordx4 v[32:35], v[152:153], off offset:3072
	s_waitcnt vmcnt(7)
	v_mul_f32_e32 v150, v61, v61
	v_mul_f32_e32 v151, v63, v63
	v_fmac_f32_e32 v150, v60, v60
	v_fmac_f32_e32 v151, v62, v62
	v_add_f32_e32 v85, v150, v151
	s_waitcnt vmcnt(6)
	v_mul_f32_e32 v150, v57, v57
	v_mul_f32_e32 v151, v59, v59
	v_fmac_f32_e32 v150, v56, v56
	v_fmac_f32_e32 v151, v58, v58
	v_add_f32_e32 v150, v150, v151
	v_add_f32_e32 v85, v85, v150
	s_waitcnt vmcnt(5)
	v_mul_f32_e32 v150, v53, v53
	v_mul_f32_e32 v151, v55, v55
	v_fmac_f32_e32 v150, v52, v52
	v_fmac_f32_e32 v151, v54, v54
	v_add_f32_e32 v150, v150, v151
	v_add_f32_e32 v85, v85, v150
	s_waitcnt vmcnt(4)
	v_mul_f32_e32 v150, v49, v49
	v_mul_f32_e32 v151, v51, v51
	v_fmac_f32_e32 v150, v48, v48
	v_fmac_f32_e32 v151, v50, v50
	v_add_f32_e32 v150, v150, v151
	v_add_f32_e32 v85, v85, v150
	s_waitcnt vmcnt(3)
	v_mul_f32_e32 v150, v45, v45
	v_mul_f32_e32 v151, v47, v47
	v_fmac_f32_e32 v150, v44, v44
	v_fmac_f32_e32 v151, v46, v46
	v_add_f32_e32 v150, v150, v151
	v_add_f32_e32 v85, v85, v150
	s_waitcnt vmcnt(2)
	v_mul_f32_e32 v150, v41, v41
	v_mul_f32_e32 v151, v43, v43
	v_fmac_f32_e32 v150, v40, v40
	v_fmac_f32_e32 v151, v42, v42
	v_add_f32_e32 v150, v150, v151
	v_add_f32_e32 v85, v85, v150
	s_waitcnt vmcnt(1)
	v_mul_f32_e32 v150, v37, v37
	v_mul_f32_e32 v151, v39, v39
	v_fmac_f32_e32 v150, v36, v36
	v_fmac_f32_e32 v151, v38, v38
	v_add_f32_e32 v150, v150, v151
	v_add_f32_e32 v85, v85, v150
	s_waitcnt vmcnt(0)
	v_mul_f32_e32 v150, v33, v33
	v_mul_f32_e32 v151, v35, v35
	v_fmac_f32_e32 v150, v32, v32
	v_fmac_f32_e32 v151, v34, v34
	v_add_f32_e32 v150, v150, v151
	v_add_f32_e32 v85, v85, v150
	ds_swizzle_b32 v87, v85 offset:swizzle(SWAP,1)
	s_waitcnt lgkmcnt(0)
	v_add_f32_e32 v85, v85, v87
	ds_swizzle_b32 v87, v85 offset:swizzle(SWAP,2)
	s_waitcnt lgkmcnt(0)
	v_add_f32_e32 v85, v85, v87
	ds_swizzle_b32 v87, v85 offset:swizzle(SWAP,4)
	s_waitcnt lgkmcnt(0)
	v_add_f32_e32 v85, v85, v87
	ds_swizzle_b32 v87, v85 offset:swizzle(SWAP,8)
	s_waitcnt lgkmcnt(0)
	v_add_f32_e32 v85, v85, v87
	ds_swizzle_b32 v87, v85 offset:swizzle(SWAP,16)
	s_waitcnt lgkmcnt(0)
	v_add_f32_e32 v85, v85, v87
	s_nop 0
	v_readlane_b32 s1, v85, 32
	v_readlane_b32 s0, v85, 0
	s_nop 0
	v_mov_b32_e32 v85, s1
	v_add_f32_e32 v85, s0, v85
	v_fmamk_f32 v85, v85, 0x3a000000, v193
	v_cmp_gt_f32_e32 vcc, s61, v85
	v_mul_f32_e32 v87, 0x4f800000, v85
	s_nop 0
	v_cndmask_b32_e32 v85, v85, v87, vcc
	v_sqrt_f32_e32 v87, v85
	s_nop 0
	v_add_u32_e32 v89, -1, v87
	v_fma_f32 v91, -v89, v87, v85
	v_cmp_ge_f32_e64 s[0:1], 0, v91
	v_add_u32_e32 v91, 1, v87
	s_nop 0
	v_cndmask_b32_e64 v89, v87, v89, s[0:1]
	v_fma_f32 v87, -v91, v87, v85
	v_cmp_lt_f32_e64 s[0:1], 0, v87
	s_nop 1
	v_cndmask_b32_e64 v87, v89, v91, s[0:1]
	v_mul_f32_e32 v89, 0x37800000, v87
	v_cndmask_b32_e32 v87, v87, v89, vcc
	v_cmp_class_f32_e32 vcc, v85, v194
	s_nop 1
	v_cndmask_b32_e32 v85, v87, v85, vcc
	v_div_scale_f32 v87, s[0:1], v85, v85, 1.0
	v_rcp_f32_e32 v89, v87
	s_nop 0
	v_fma_f32 v91, -v87, v89, 1.0
	v_fmac_f32_e32 v89, v91, v89
	v_div_scale_f32 v91, vcc, 1.0, v85, 1.0
	v_mul_f32_e32 v93, v91, v89
	v_fma_f32 v95, -v87, v93, v91
	v_fmac_f32_e32 v93, v95, v89
	v_fma_f32 v87, -v87, v93, v91
	v_div_fmas_f32 v87, v87, v89, v93
	v_div_fixup_f32 v140, v87, v85, 1.0
	v_pk_mul_f32 v[60:61], v[60:61], v[140:141] op_sel_hi:[1,0]
	v_pk_mul_f32 v[62:63], v[62:63], v[140:141] op_sel_hi:[1,0]
	v_pk_fma_f32 v[60:61], v[104:105], v[60:61], v[0:1]
	v_pk_fma_f32 v[62:63], v[102:103], v[62:63], v[2:3]
	v_bfe_u32 v85, v60, 16, 1
	v_add3_u32 v60, v60, v85, s72
	v_bfe_u32 v85, v61, 16, 1
	v_lshrrev_b32_e32 v60, 16, v60
	v_add3_u32 v61, v61, v85, s72
	v_and_or_b32 v60, v61, s73, v60
	v_bfe_u32 v61, v62, 16, 1
	v_add3_u32 v61, v62, v61, s72
	v_bfe_u32 v62, v63, 16, 1
	v_lshrrev_b32_e32 v61, 16, v61
	v_add3_u32 v62, v63, v62, s72
	v_pk_mul_f32 v[56:57], v[56:57], v[140:141] op_sel_hi:[1,0]
	v_and_or_b32 v61, v62, s73, v61
	v_lshl_add_u64 v[62:63], v[80:81], 0, v[142:143]
	v_pk_fma_f32 v[56:57], v[108:109], v[56:57], v[4:5]
	global_store_dwordx2 v[62:63], v[60:61], off
	v_bfe_u32 v60, v56, 16, 1
	v_pk_mul_f32 v[58:59], v[58:59], v[140:141] op_sel_hi:[1,0]
	v_add3_u32 v56, v56, v60, s72
	v_bfe_u32 v60, v57, 16, 1
	v_pk_fma_f32 v[58:59], v[106:107], v[58:59], v[6:7]
	v_lshrrev_b32_e32 v56, 16, v56
	v_add3_u32 v57, v57, v60, s72
	v_and_or_b32 v56, v57, s73, v56
	v_bfe_u32 v57, v58, 16, 1
	v_add3_u32 v57, v58, v57, s72
	v_bfe_u32 v58, v59, 16, 1
	v_lshrrev_b32_e32 v57, 16, v57
	v_add3_u32 v58, v59, v58, s72
	v_pk_mul_f32 v[52:53], v[52:53], v[140:141] op_sel_hi:[1,0]
	v_and_or_b32 v57, v58, s73, v57
	v_pk_fma_f32 v[52:53], v[112:113], v[52:53], v[8:9]
	global_store_dwordx2 v[62:63], v[56:57], off offset:512
	v_bfe_u32 v56, v52, 16, 1
; __device__ __forceinline__ unsigned pk2(float lo, float hi) { return f2bf(lo) | (f2bf(hi) << 16); }
; template <int SRC> __device__ __forceinline__ void prenorm_rows(const LArgs& a, int nrows, const float* nw, const float* mods_layer, int shift_part, bf16* dst) {
;     ...
;         for (int r = 0; r < 16; ++r) {
;             const float* src = src0 + (size_t)r * DM; f32x4 v[8]; float ss = 0.f;
; #pragma unroll
;             for (int j = 0; j < 8; ++j) { v[j] = *(const f32x4*)(src + 4 * lane + 256 * j); ss += (v[j].x * v[j].x + v[j].y * v[j].y) + (v[j].z * v[j].z + v[j].w * v[j].w); }
;     ...
; #pragma unroll
;             for (int j = 0; j < 8; ++j) { const int col = 4 * lane + 256 * j; const f32x4 o = v[j] * rn * cs[j] + sv[j]; u32x2 pq; pq.x = pk2(o.x, o.y); pq.y = pk2(o.z, o.w); *(u32x2*)(dst + (size_t)(row0 + r) * DM + col) = pq; }
	v_pk_mul_f32 v[54:55], v[54:55], v[140:141] op_sel_hi:[1,0]
	v_add3_u32 v52, v52, v56, s72
	v_bfe_u32 v56, v53, 16, 1
	v_pk_fma_f32 v[54:55], v[110:111], v[54:55], v[10:11]
	v_lshrrev_b32_e32 v52, 16, v52
	v_add3_u32 v53, v53, v56, s72
	v_and_or_b32 v52, v53, s73, v52
	v_bfe_u32 v53, v54, 16, 1
	v_add3_u32 v53, v54, v53, s72
	v_bfe_u32 v54, v55, 16, 1
	v_lshrrev_b32_e32 v53, 16, v53
	v_add3_u32 v54, v55, v54, s72
	v_pk_mul_f32 v[48:49], v[48:49], v[140:141] op_sel_hi:[1,0]
	v_and_or_b32 v53, v54, s73, v53
	v_pk_fma_f32 v[48:49], v[116:117], v[48:49], v[12:13]
	global_store_dwordx2 v[62:63], v[52:53], off offset:1024
	v_bfe_u32 v52, v48, 16, 1
	v_pk_mul_f32 v[50:51], v[50:51], v[140:141] op_sel_hi:[1,0]
	v_add3_u32 v48, v48, v52, s72
	v_bfe_u32 v52, v49, 16, 1
	v_pk_fma_f32 v[50:51], v[114:115], v[50:51], v[14:15]
	v_lshrrev_b32_e32 v48, 16, v48
	v_add3_u32 v49, v49, v52, s72
	v_and_or_b32 v48, v49, s73, v48
	v_bfe_u32 v49, v50, 16, 1
	v_add3_u32 v49, v50, v49, s72
	v_bfe_u32 v50, v51, 16, 1
	v_lshrrev_b32_e32 v49, 16, v49
	v_add3_u32 v50, v51, v50, s72
	v_pk_mul_f32 v[44:45], v[44:45], v[140:141] op_sel_hi:[1,0]
	v_and_or_b32 v49, v50, s73, v49
	v_pk_fma_f32 v[44:45], v[120:121], v[44:45], v[16:17]
	global_store_dwordx2 v[62:63], v[48:49], off offset:1536
	v_bfe_u32 v48, v44, 16, 1
	v_pk_mul_f32 v[46:47], v[46:47], v[140:141] op_sel_hi:[1,0]
	v_add3_u32 v44, v44, v48, s72
	v_bfe_u32 v48, v45, 16, 1
	v_pk_fma_f32 v[46:47], v[118:119], v[46:47], v[18:19]
	v_lshrrev_b32_e32 v44, 16, v44
	v_add3_u32 v45, v45, v48, s72
	v_and_or_b32 v44, v45, s73, v44
	v_bfe_u32 v45, v46, 16, 1
	v_add3_u32 v45, v46, v45, s72
	v_bfe_u32 v46, v47, 16, 1
	v_lshrrev_b32_e32 v45, 16, v45
	v_add3_u32 v46, v47, v46, s72
	v_pk_mul_f32 v[40:41], v[40:41], v[140:141] op_sel_hi:[1,0]
	v_and_or_b32 v45, v46, s73, v45
	v_pk_fma_f32 v[40:41], v[124:125], v[40:41], v[20:21]
	global_store_dwordx2 v[62:63], v[44:45], off offset:2048
	v_bfe_u32 v44, v40, 16, 1
	v_pk_mul_f32 v[42:43], v[42:43], v[140:141] op_sel_hi:[1,0]
	v_add3_u32 v40, v40, v44, s72
	v_bfe_u32 v44, v41, 16, 1
	v_pk_fma_f32 v[42:43], v[122:123], v[42:43], v[22:23]
	v_lshrrev_b32_e32 v40, 16, v40
	v_add3_u32 v41, v41, v44, s72
	v_and_or_b32 v40, v41, s73, v40
	v_bfe_u32 v41, v42, 16, 1
	v_add3_u32 v41, v42, v41, s72
	v_bfe_u32 v42, v43, 16, 1
	v_lshrrev_b32_e32 v41, 16, v41
	v_add3_u32 v42, v43, v42, s72
	v_pk_mul_f32 v[36:37], v[36:37], v[140:141] op_sel_hi:[1,0]
	v_and_or_b32 v41, v42, s73, v41
	v_pk_fma_f32 v[36:37], v[128:129], v[36:37], v[24:25]
	global_store_dwordx2 v[62:63], v[40:41], off offset:2560
	v_bfe_u32 v40, v36, 16, 1
	v_pk_mul_f32 v[38:39], v[38:39], v[140:141] op_sel_hi:[1,0]
	v_add3_u32 v36, v36, v40, s72
	v_bfe_u32 v40, v37, 16, 1
	v_pk_fma_f32 v[38:39], v[126:127], v[38:39], v[26:27]
	v_lshrrev_b32_e32 v36, 16, v36
	v_add3_u32 v37, v37, v40, s72
	v_and_or_b32 v36, v37, s73, v36
	v_bfe_u32 v37, v38, 16, 1
	v_add3_u32 v37, v38, v37, s72
	v_bfe_u32 v38, v39, 16, 1
	v_lshrrev_b32_e32 v37, 16, v37
	v_add3_u32 v38, v39, v38, s72
	v_pk_mul_f32 v[32:33], v[32:33], v[140:141] op_sel_hi:[1,0]
	v_and_or_b32 v37, v38, s73, v37
	v_pk_fma_f32 v[32:33], v[132:133], v[32:33], v[28:29]
	global_store_dwordx2 v[62:63], v[36:37], off offset:3072
	v_bfe_u32 v36, v32, 16, 1
	v_pk_mul_f32 v[34:35], v[34:35], v[140:141] op_sel_hi:[1,0]
	v_add3_u32 v32, v32, v36, s72
	v_bfe_u32 v36, v33, 16, 1
	v_pk_fma_f32 v[34:35], v[130:131], v[34:35], v[30:31]
	v_lshrrev_b32_e32 v32, 16, v32
	v_add3_u32 v33, v33, v36, s72
	v_and_or_b32 v32, v33, s73, v32
	v_bfe_u32 v33, v34, 16, 1
	v_add3_u32 v33, v34, v33, s72
	v_bfe_u32 v34, v35, 16, 1
	v_lshrrev_b32_e32 v33, 16, v33
	v_add3_u32 v34, v35, v34, s72
	v_and_or_b32 v33, v34, s73, v33
	global_store_dwordx2 v[62:63], v[32:33], off offset:3584
	global_load_dwordx4 v[60:63], v[138:139], off
	global_load_dwordx4 v[56:59], v[138:139], off offset:1024
	global_load_dwordx4 v[52:55], v[138:139], off offset:2048
	global_load_dwordx4 v[48:51], v[138:139], off offset:3072
	v_add_co_u32_e32 v154, vcc, s33, v136
	s_nop 1
	v_addc_co_u32_e32 v155, vcc, 0, v137, vcc
	global_load_dwordx4 v[44:47], v[154:155], off
	global_load_dwordx4 v[40:43], v[154:155], off offset:1024
	global_load_dwordx4 v[36:39], v[154:155], off offset:2048
	global_load_dwordx4 v[32:35], v[154:155], off offset:3072
	s_nop 0
	v_add_u32_e32 v138, 1, v134
	v_ashrrev_i32_e32 v139, 31, v138
	v_lshlrev_b64 v[138:139], 12, v[138:139]
	v_add_u32_e32 v134, 2, v134
	s_nop 1
	s_waitcnt vmcnt(7)
	v_mul_f32_e32 v150, v61, v61
	v_mul_f32_e32 v151, v63, v63
	v_fmac_f32_e32 v150, v60, v60
	v_fmac_f32_e32 v151, v62, v62
	v_add_f32_e32 v85, v150, v151
	s_waitcnt vmcnt(6)
	v_mul_f32_e32 v150, v57, v57
	v_mul_f32_e32 v151, v59, v59
	v_fmac_f32_e32 v150, v56, v56
	v_fmac_f32_e32 v151, v58, v58
	v_add_f32_e32 v150, v150, v151
	v_add_f32_e32 v85, v85, v150
	s_waitcnt vmcnt(5)
	v_mul_f32_e32 v150, v53, v53
	v_mul_f32_e32 v151, v55, v55
	v_fmac_f32_e32 v150, v52, v52
	v_fmac_f32_e32 v151, v54, v54
	v_add_f32_e32 v150, v150, v151
	v_add_f32_e32 v85, v85, v150
	s_waitcnt vmcnt(4)
	v_mul_f32_e32 v150, v49, v49
	v_mul_f32_e32 v151, v51, v51
	v_fmac_f32_e32 v150, v48, v48
	v_fmac_f32_e32 v151, v50, v50
	v_add_f32_e32 v150, v150, v151
	v_add_f32_e32 v85, v85, v150
	s_waitcnt vmcnt(3)
	v_mul_f32_e32 v150, v45, v45
	v_mul_f32_e32 v151, v47, v47
	v_fmac_f32_e32 v150, v44, v44
	v_fmac_f32_e32 v151, v46, v46
	v_add_f32_e32 v150, v150, v151
	v_add_f32_e32 v85, v85, v150
	s_waitcnt vmcnt(2)
	v_mul_f32_e32 v150, v41, v41
	v_mul_f32_e32 v151, v43, v43
	v_fmac_f32_e32 v150, v40, v40
	v_fmac_f32_e32 v151, v42, v42
	v_add_f32_e32 v150, v150, v151
	v_add_f32_e32 v85, v85, v150
	s_waitcnt vmcnt(1)
; template <int SRC> __device__ __forceinline__ void prenorm_rows(const LArgs& a, int nrows, const float* nw, const float* mods_layer, int shift_part, bf16* dst) {
;     ...
;             for (int j = 0; j < 8; ++j) { v[j] = *(const f32x4*)(src + 4 * lane + 256 * j); ss += (v[j].x * v[j].x + v[j].y * v[j].y) + (v[j].z * v[j].z + v[j].w * v[j].w); }
;             const float rn = 1.f / sqrtf(wave_sum(ss) * (1.f / DM) + 1e-6f);
	v_mul_f32_e32 v150, v37, v37
	v_mul_f32_e32 v151, v39, v39
	v_fmac_f32_e32 v150, v36, v36
	v_fmac_f32_e32 v151, v38, v38
	v_add_f32_e32 v150, v150, v151
	v_add_f32_e32 v85, v85, v150
	s_waitcnt vmcnt(0)
	v_mul_f32_e32 v150, v33, v33
	v_mul_f32_e32 v151, v35, v35
	v_fmac_f32_e32 v150, v32, v32
	v_fmac_f32_e32 v151, v34, v34
	v_add_f32_e32 v150, v150, v151
	v_add_f32_e32 v85, v85, v150
	ds_swizzle_b32 v87, v85 offset:swizzle(SWAP,1)
	s_waitcnt lgkmcnt(0)
	v_add_f32_e32 v85, v85, v87
	ds_swizzle_b32 v87, v85 offset:swizzle(SWAP,2)
	s_waitcnt lgkmcnt(0)
	v_add_f32_e32 v85, v85, v87
	ds_swizzle_b32 v87, v85 offset:swizzle(SWAP,4)
	s_waitcnt lgkmcnt(0)
	v_add_f32_e32 v85, v85, v87
	ds_swizzle_b32 v87, v85 offset:swizzle(SWAP,8)
	s_waitcnt lgkmcnt(0)
	v_add_f32_e32 v85, v85, v87
	ds_swizzle_b32 v87, v85 offset:swizzle(SWAP,16)
	s_waitcnt lgkmcnt(0)
; __device__ __forceinline__ unsigned pk2(float lo, float hi) { return f2bf(lo) | (f2bf(hi) << 16); }
; template <int SRC> __device__ __forceinline__ void prenorm_rows(const LArgs& a, int nrows, const float* nw, const float* mods_layer, int shift_part, bf16* dst) {
;     ...
;     for (int chunk = gw; chunk < nrows / 16; chunk += NGW) {
;     ...
;             const float rn = 1.f / sqrtf(wave_sum(ss) * (1.f / DM) + 1e-6f);
; #pragma unroll
;             for (int j = 0; j < 8; ++j) { const int col = 4 * lane + 256 * j; const f32x4 o = v[j] * rn * cs[j] + sv[j]; u32x2 pq; pq.x = pk2(o.x, o.y); pq.y = pk2(o.z, o.w); *(u32x2*)(dst + (size_t)(row0 + r) * DM + col) = pq; }
;         }
	v_add_f32_e32 v85, v85, v87
	s_nop 0
	v_readlane_b32 s1, v85, 32
	v_readlane_b32 s0, v85, 0
	s_nop 0
	v_mov_b32_e32 v85, s1
	v_add_f32_e32 v85, s0, v85
	v_fmamk_f32 v85, v85, 0x3a000000, v193
	v_cmp_gt_f32_e32 vcc, s61, v85
	v_mul_f32_e32 v87, 0x4f800000, v85
	s_nop 0
	v_cndmask_b32_e32 v85, v85, v87, vcc
	v_sqrt_f32_e32 v87, v85
	s_nop 0
	v_add_u32_e32 v89, -1, v87
	v_fma_f32 v91, -v89, v87, v85
	v_cmp_ge_f32_e64 s[0:1], 0, v91
	v_add_u32_e32 v91, 1, v87
	s_nop 0
	v_cndmask_b32_e64 v89, v87, v89, s[0:1]
	v_fma_f32 v87, -v91, v87, v85
	v_cmp_lt_f32_e64 s[0:1], 0, v87
	s_nop 1
	v_cndmask_b32_e64 v87, v89, v91, s[0:1]
	v_mul_f32_e32 v89, 0x37800000, v87
	v_cndmask_b32_e32 v87, v87, v89, vcc
	v_cmp_class_f32_e32 vcc, v85, v194
	s_nop 1
	v_cndmask_b32_e32 v85, v87, v85, vcc
	v_div_scale_f32 v87, s[0:1], v85, v85, 1.0
	v_rcp_f32_e32 v89, v87
	s_nop 0
	v_fma_f32 v91, -v87, v89, 1.0
	v_fmac_f32_e32 v89, v91, v89
	v_div_scale_f32 v91, vcc, 1.0, v85, 1.0
	v_mul_f32_e32 v93, v91, v89
	v_fma_f32 v95, -v87, v93, v91
	v_fmac_f32_e32 v93, v95, v89
	v_fma_f32 v87, -v87, v93, v91
	v_div_fmas_f32 v87, v87, v89, v93
	v_div_fixup_f32 v136, v87, v85, 1.0
	v_pk_mul_f32 v[60:61], v[60:61], v[136:137] op_sel_hi:[1,0]
	v_pk_mul_f32 v[62:63], v[62:63], v[136:137] op_sel_hi:[1,0]
	v_pk_fma_f32 v[60:61], v[104:105], v[60:61], v[0:1]
	v_pk_fma_f32 v[62:63], v[102:103], v[62:63], v[2:3]
	v_bfe_u32 v85, v60, 16, 1
	v_add3_u32 v60, v60, v85, s72
	v_bfe_u32 v85, v61, 16, 1
	v_lshrrev_b32_e32 v60, 16, v60
	v_add3_u32 v61, v61, v85, s72
	v_and_or_b32 v60, v61, s73, v60
	v_bfe_u32 v61, v62, 16, 1
	v_add3_u32 v61, v62, v61, s72
	v_bfe_u32 v62, v63, 16, 1
	v_lshrrev_b32_e32 v61, 16, v61
	v_add3_u32 v62, v63, v62, s72
	v_pk_mul_f32 v[56:57], v[56:57], v[136:137] op_sel_hi:[1,0]
	v_and_or_b32 v61, v62, s73, v61
	v_lshl_add_u64 v[62:63], v[80:81], 0, v[138:139]
	v_pk_fma_f32 v[56:57], v[108:109], v[56:57], v[4:5]
	global_store_dwordx2 v[62:63], v[60:61], off
	v_bfe_u32 v60, v56, 16, 1
	v_pk_mul_f32 v[58:59], v[58:59], v[136:137] op_sel_hi:[1,0]
	v_add3_u32 v56, v56, v60, s72
	v_bfe_u32 v60, v57, 16, 1
	v_pk_fma_f32 v[58:59], v[106:107], v[58:59], v[6:7]
	v_lshrrev_b32_e32 v56, 16, v56
	v_add3_u32 v57, v57, v60, s72
	v_and_or_b32 v56, v57, s73, v56
	v_bfe_u32 v57, v58, 16, 1
	v_add3_u32 v57, v58, v57, s72
	v_bfe_u32 v58, v59, 16, 1
	v_lshrrev_b32_e32 v57, 16, v57
	v_add3_u32 v58, v59, v58, s72
	v_pk_mul_f32 v[52:53], v[52:53], v[136:137] op_sel_hi:[1,0]
	v_and_or_b32 v57, v58, s73, v57
	v_pk_fma_f32 v[52:53], v[112:113], v[52:53], v[8:9]
	global_store_dwordx2 v[62:63], v[56:57], off offset:512
	v_bfe_u32 v56, v52, 16, 1
	v_pk_mul_f32 v[54:55], v[54:55], v[136:137] op_sel_hi:[1,0]
	v_add3_u32 v52, v52, v56, s72
	v_bfe_u32 v56, v53, 16, 1
	v_pk_fma_f32 v[54:55], v[110:111], v[54:55], v[10:11]
	v_lshrrev_b32_e32 v52, 16, v52
	v_add3_u32 v53, v53, v56, s72
	v_and_or_b32 v52, v53, s73, v52
	v_bfe_u32 v53, v54, 16, 1
	v_add3_u32 v53, v54, v53, s72
	v_bfe_u32 v54, v55, 16, 1
	v_lshrrev_b32_e32 v53, 16, v53
	v_add3_u32 v54, v55, v54, s72
	v_pk_mul_f32 v[48:49], v[48:49], v[136:137] op_sel_hi:[1,0]
	v_and_or_b32 v53, v54, s73, v53
	v_pk_fma_f32 v[48:49], v[116:117], v[48:49], v[12:13]
	global_store_dwordx2 v[62:63], v[52:53], off offset:1024
	v_bfe_u32 v52, v48, 16, 1
	v_pk_mul_f32 v[50:51], v[50:51], v[136:137] op_sel_hi:[1,0]
	v_add3_u32 v48, v48, v52, s72
	v_bfe_u32 v52, v49, 16, 1
	v_pk_fma_f32 v[50:51], v[114:115], v[50:51], v[14:15]
	v_lshrrev_b32_e32 v48, 16, v48
	v_add3_u32 v49, v49, v52, s72
	v_and_or_b32 v48, v49, s73, v48
	v_bfe_u32 v49, v50, 16, 1
	v_add3_u32 v49, v50, v49, s72
	v_bfe_u32 v50, v51, 16, 1
	v_lshrrev_b32_e32 v49, 16, v49
	v_add3_u32 v50, v51, v50, s72
	v_pk_mul_f32 v[44:45], v[44:45], v[136:137] op_sel_hi:[1,0]
	v_and_or_b32 v49, v50, s73, v49
	v_pk_fma_f32 v[44:45], v[120:121], v[44:45], v[16:17]
	global_store_dwordx2 v[62:63], v[48:49], off offset:1536
	v_bfe_u32 v48, v44, 16, 1
	v_pk_mul_f32 v[46:47], v[46:47], v[136:137] op_sel_hi:[1,0]
	v_add3_u32 v44, v44, v48, s72
	v_bfe_u32 v48, v45, 16, 1
	v_pk_fma_f32 v[46:47], v[118:119], v[46:47], v[18:19]
	v_lshrrev_b32_e32 v44, 16, v44
	v_add3_u32 v45, v45, v48, s72
	v_and_or_b32 v44, v45, s73, v44
	v_bfe_u32 v45, v46, 16, 1
	v_add3_u32 v45, v46, v45, s72
	v_bfe_u32 v46, v47, 16, 1
	v_lshrrev_b32_e32 v45, 16, v45
	v_add3_u32 v46, v47, v46, s72
	v_pk_mul_f32 v[40:41], v[40:41], v[136:137] op_sel_hi:[1,0]
	v_and_or_b32 v45, v46, s73, v45
	v_pk_fma_f32 v[40:41], v[124:125], v[40:41], v[20:21]
	global_store_dwordx2 v[62:63], v[44:45], off offset:2048
	v_bfe_u32 v44, v40, 16, 1
	v_pk_mul_f32 v[42:43], v[42:43], v[136:137] op_sel_hi:[1,0]
	v_add3_u32 v40, v40, v44, s72
	v_bfe_u32 v44, v41, 16, 1
	v_pk_fma_f32 v[42:43], v[122:123], v[42:43], v[22:23]
	v_lshrrev_b32_e32 v40, 16, v40
	v_add3_u32 v41, v41, v44, s72
	v_and_or_b32 v40, v41, s73, v40
	v_bfe_u32 v41, v42, 16, 1
	v_add3_u32 v41, v42, v41, s72
	v_bfe_u32 v42, v43, 16, 1
	v_lshrrev_b32_e32 v41, 16, v41
	v_add3_u32 v42, v43, v42, s72
	v_pk_mul_f32 v[36:37], v[36:37], v[136:137] op_sel_hi:[1,0]
	v_and_or_b32 v41, v42, s73, v41
	v_pk_fma_f32 v[36:37], v[128:129], v[36:37], v[24:25]
	global_store_dwordx2 v[62:63], v[40:41], off offset:2560
	v_bfe_u32 v40, v36, 16, 1
	v_pk_mul_f32 v[38:39], v[38:39], v[136:137] op_sel_hi:[1,0]
	v_add3_u32 v36, v36, v40, s72
	v_bfe_u32 v40, v37, 16, 1
	v_pk_fma_f32 v[38:39], v[126:127], v[38:39], v[26:27]
	v_lshrrev_b32_e32 v36, 16, v36
	v_add3_u32 v37, v37, v40, s72
	v_and_or_b32 v36, v37, s73, v36
	v_bfe_u32 v37, v38, 16, 1
	v_add3_u32 v37, v38, v37, s72
	v_bfe_u32 v38, v39, 16, 1
	v_lshrrev_b32_e32 v37, 16, v37
	v_add3_u32 v38, v39, v38, s72
	v_pk_mul_f32 v[32:33], v[32:33], v[136:137] op_sel_hi:[1,0]
	v_and_or_b32 v37, v38, s73, v37
	v_pk_fma_f32 v[32:33], v[132:133], v[32:33], v[28:29]
	global_store_dwordx2 v[62:63], v[36:37], off offset:3072
	v_bfe_u32 v36, v32, 16, 1
	v_pk_mul_f32 v[34:35], v[34:35], v[136:137] op_sel_hi:[1,0]
	v_add3_u32 v32, v32, v36, s72
	v_bfe_u32 v36, v33, 16, 1
	v_pk_fma_f32 v[34:35], v[130:131], v[34:35], v[30:31]
	v_lshrrev_b32_e32 v32, 16, v32
	v_add3_u32 v33, v33, v36, s72
	v_and_or_b32 v32, v33, s73, v32
	v_bfe_u32 v33, v34, 16, 1
	v_add3_u32 v33, v34, v33, s72
	v_bfe_u32 v34, v35, 16, 1
	v_lshrrev_b32_e32 v33, 16, v33
	v_add3_u32 v34, v35, v34, s72
	v_and_or_b32 v33, v34, s73, v33
	global_store_dwordx2 v[62:63], v[32:33], off offset:3584
	s_cbranch_scc0 .LBB0_234
	v_add_u32_e32 v141, s86, v141
	v_cmp_lt_i32_e32 vcc, s82, v141
	v_readlane_b32 s0, v254, 6
	s_or_b64 s[6:7], vcc, s[6:7]
	s_nop 0
	v_add_u32_e32 v84, s0, v84
	s_andn2_b64 exec, exec, s[6:7]
	s_cbranch_execnz .LBB0_233

; template <int SRC> __device__ __forceinline__ void prenorm_rows(const LArgs& a, int nrows, const float* nw, const float* mods_layer, int shift_part, bf16* dst) {
;     ...
;         for (int r = 0; r < 16; ++r) {
;             const float* src = src0 + (size_t)r * DM; f32x4 v[8]; float ss = 0.f;
; #pragma unroll
;             for (int j = 0; j < 8; ++j) { v[j] = *(const f32x4*)(src + 4 * lane + 256 * j); ss += (v[j].x * v[j].x + v[j].y * v[j].y) + (v[j].z * v[j].z + v[j].w * v[j].w); }
;             const float rn = 1.f / sqrtf(wave_sum(ss) * (1.f / DM) + 1e-6f);
.LBB0_269:
	v_lshl_add_u64 v[130:131], v[94:95], 0, s[12:13]
	v_add_co_u32_e32 v32, vcc, 0xd000000, v130
	v_ashrrev_i32_e32 v129, 31, v128
	s_nop 0
	v_addc_co_u32_e32 v33, vcc, 0, v131, vcc
	v_lshlrev_b64 v[136:137], 12, v[128:129]
	s_add_u32 s12, s12, 0x4000
	s_addc_u32 s13, s13, 0
	s_cmp_eq_u32 s12, 0x20000
	s_nop 1
	v_add_co_u32_e32 v132, vcc, s63, v130
	s_nop 1
	s_nop 0
	v_addc_co_u32_e32 v133, vcc, 0, v131, vcc
	v_add_co_u32_e32 v152, vcc, s60, v130
	s_nop 1
	v_addc_co_u32_e32 v153, vcc, 0, v131, vcc
	global_load_dwordx4 v[60:63], v[32:33], off
	global_load_dwordx4 v[56:59], v[32:33], off offset:1024
	global_load_dwordx4 v[52:55], v[32:33], off offset:2048
	global_load_dwordx4 v[48:51], v[32:33], off offset:3072
	global_load_dwordx4 v[44:47], v[152:153], off
	global_load_dwordx4 v[40:43], v[152:153], off offset:1024
	global_load_dwordx4 v[36:39], v[152:153], off offset:2048
	global_load_dwordx4 v[32:35], v[152:153], off offset:3072
	s_waitcnt vmcnt(7)
	v_mul_f32_e32 v150, v61, v61
	v_mul_f32_e32 v151, v63, v63
	v_fmac_f32_e32 v150, v60, v60
	v_fmac_f32_e32 v151, v62, v62
	v_add_f32_e32 v79, v150, v151
	s_waitcnt vmcnt(6)
	v_mul_f32_e32 v150, v57, v57
	v_mul_f32_e32 v151, v59, v59
	v_fmac_f32_e32 v150, v56, v56
	v_fmac_f32_e32 v151, v58, v58
	v_add_f32_e32 v150, v150, v151
	v_add_f32_e32 v79, v79, v150
	s_waitcnt vmcnt(5)
	v_mul_f32_e32 v150, v53, v53
	v_mul_f32_e32 v151, v55, v55
	v_fmac_f32_e32 v150, v52, v52
	v_fmac_f32_e32 v151, v54, v54
	v_add_f32_e32 v150, v150, v151
	v_add_f32_e32 v79, v79, v150
	s_waitcnt vmcnt(4)
	v_mul_f32_e32 v150, v49, v49
	v_mul_f32_e32 v151, v51, v51
	v_fmac_f32_e32 v150, v48, v48
	v_fmac_f32_e32 v151, v50, v50
	v_add_f32_e32 v150, v150, v151
	v_add_f32_e32 v79, v79, v150
	s_waitcnt vmcnt(3)
	v_mul_f32_e32 v150, v45, v45
	v_mul_f32_e32 v151, v47, v47
	v_fmac_f32_e32 v150, v44, v44
	v_fmac_f32_e32 v151, v46, v46
	v_add_f32_e32 v150, v150, v151
	v_add_f32_e32 v79, v79, v150
	s_waitcnt vmcnt(2)
	v_mul_f32_e32 v150, v41, v41
	v_mul_f32_e32 v151, v43, v43
	v_fmac_f32_e32 v150, v40, v40
	v_fmac_f32_e32 v151, v42, v42
	v_add_f32_e32 v150, v150, v151
	v_add_f32_e32 v79, v79, v150
	s_waitcnt vmcnt(1)
	v_mul_f32_e32 v150, v37, v37
	v_mul_f32_e32 v151, v39, v39
	v_fmac_f32_e32 v150, v36, v36
	v_fmac_f32_e32 v151, v38, v38
	v_add_f32_e32 v150, v150, v151
	v_add_f32_e32 v79, v79, v150
	s_waitcnt vmcnt(0)
	v_mul_f32_e32 v150, v33, v33
	v_mul_f32_e32 v151, v35, v35
	v_fmac_f32_e32 v150, v32, v32
	v_fmac_f32_e32 v151, v34, v34
	v_add_f32_e32 v150, v150, v151
	v_add_f32_e32 v79, v79, v150
	ds_swizzle_b32 v81, v79 offset:swizzle(SWAP,1)
	s_waitcnt lgkmcnt(0)
	v_add_f32_e32 v79, v79, v81
	ds_swizzle_b32 v81, v79 offset:swizzle(SWAP,2)
	s_waitcnt lgkmcnt(0)
	v_add_f32_e32 v79, v79, v81
	ds_swizzle_b32 v81, v79 offset:swizzle(SWAP,4)
	s_waitcnt lgkmcnt(0)
	v_add_f32_e32 v79, v79, v81
	ds_swizzle_b32 v81, v79 offset:swizzle(SWAP,8)
	s_waitcnt lgkmcnt(0)
	v_add_f32_e32 v79, v79, v81
	ds_swizzle_b32 v81, v79 offset:swizzle(SWAP,16)
	s_waitcnt lgkmcnt(0)
	v_add_f32_e32 v79, v79, v81
	s_nop 0
	v_readlane_b32 s1, v79, 32
	v_readlane_b32 s0, v79, 0
	s_nop 0
	v_mov_b32_e32 v79, s1
	v_add_f32_e32 v79, s0, v79
	v_fmamk_f32 v79, v79, 0x3a000000, v193
	v_cmp_gt_f32_e32 vcc, s61, v79
	v_mul_f32_e32 v81, 0x4f800000, v79
	s_nop 0
	v_cndmask_b32_e32 v79, v79, v81, vcc
	v_sqrt_f32_e32 v81, v79
	s_nop 0
	v_add_u32_e32 v83, -1, v81
	v_fma_f32 v85, -v83, v81, v79
	v_cmp_ge_f32_e64 s[0:1], 0, v85
	v_add_u32_e32 v85, 1, v81
	s_nop 0
	v_cndmask_b32_e64 v83, v81, v83, s[0:1]
	v_fma_f32 v81, -v85, v81, v79
	v_cmp_lt_f32_e64 s[0:1], 0, v81
	s_nop 1
	v_cndmask_b32_e64 v81, v83, v85, s[0:1]
	v_mul_f32_e32 v83, 0x37800000, v81
	v_cndmask_b32_e32 v81, v81, v83, vcc
	v_cmp_class_f32_e32 vcc, v79, v194
	s_nop 1
	v_cndmask_b32_e32 v79, v81, v79, vcc
	v_div_scale_f32 v81, s[0:1], v79, v79, 1.0
	v_rcp_f32_e32 v83, v81
	s_nop 0
	v_fma_f32 v85, -v81, v83, 1.0
	v_fmac_f32_e32 v83, v85, v83
	v_div_scale_f32 v85, vcc, 1.0, v79, 1.0
	v_mul_f32_e32 v87, v85, v83
	v_fma_f32 v89, -v81, v87, v85
	v_fmac_f32_e32 v87, v89, v83
	v_fma_f32 v81, -v81, v87, v85
	v_div_fmas_f32 v81, v81, v83, v87
	v_div_fixup_f32 v134, v81, v79, 1.0
	v_pk_mul_f32 v[60:61], v[60:61], v[134:135] op_sel_hi:[1,0]
	v_pk_mul_f32 v[62:63], v[62:63], v[134:135] op_sel_hi:[1,0]
	v_pk_fma_f32 v[60:61], v[98:99], v[60:61], v[0:1]
	v_pk_fma_f32 v[62:63], v[96:97], v[62:63], v[2:3]
	v_bfe_u32 v79, v60, 16, 1
	v_add3_u32 v60, v60, v79, s72
	v_bfe_u32 v79, v61, 16, 1
	v_lshrrev_b32_e32 v60, 16, v60
	v_add3_u32 v61, v61, v79, s72
	v_and_or_b32 v60, v61, s73, v60
	v_bfe_u32 v61, v62, 16, 1
	v_add3_u32 v61, v62, v61, s72
	v_bfe_u32 v62, v63, 16, 1
	v_lshrrev_b32_e32 v61, 16, v61
	v_add3_u32 v62, v63, v62, s72
	v_pk_mul_f32 v[56:57], v[56:57], v[134:135] op_sel_hi:[1,0]
	v_and_or_b32 v61, v62, s73, v61
	v_lshl_add_u64 v[62:63], v[74:75], 0, v[136:137]
	v_pk_fma_f32 v[56:57], v[102:103], v[56:57], v[4:5]
	global_store_dwordx2 v[62:63], v[60:61], off
	v_bfe_u32 v60, v56, 16, 1
	v_pk_mul_f32 v[58:59], v[58:59], v[134:135] op_sel_hi:[1,0]
	v_add3_u32 v56, v56, v60, s72
	v_bfe_u32 v60, v57, 16, 1
	v_pk_fma_f32 v[58:59], v[100:101], v[58:59], v[6:7]
	v_lshrrev_b32_e32 v56, 16, v56
	v_add3_u32 v57, v57, v60, s72
	v_and_or_b32 v56, v57, s73, v56
	v_bfe_u32 v57, v58, 16, 1
	v_add3_u32 v57, v58, v57, s72
	v_bfe_u32 v58, v59, 16, 1
	v_lshrrev_b32_e32 v57, 16, v57
	v_add3_u32 v58, v59, v58, s72
	v_pk_mul_f32 v[52:53], v[52:53], v[134:135] op_sel_hi:[1,0]
	v_and_or_b32 v57, v58, s73, v57
	v_pk_fma_f32 v[52:53], v[106:107], v[52:53], v[8:9]
	global_store_dwordx2 v[62:63], v[56:57], off offset:512
	v_bfe_u32 v56, v52, 16, 1
; __device__ __forceinline__ unsigned pk2(float lo, float hi) { return f2bf(lo) | (f2bf(hi) << 16); }
; template <int SRC> __device__ __forceinline__ void prenorm_rows(const LArgs& a, int nrows, const float* nw, const float* mods_layer, int shift_part, bf16* dst) {
;     ...
;         for (int r = 0; r < 16; ++r) {
;             const float* src = src0 + (size_t)r * DM; f32x4 v[8]; float ss = 0.f;
; #pragma unroll
;             for (int j = 0; j < 8; ++j) { v[j] = *(const f32x4*)(src + 4 * lane + 256 * j); ss += (v[j].x * v[j].x + v[j].y * v[j].y) + (v[j].z * v[j].z + v[j].w * v[j].w); }
;     ...
; #pragma unroll
;             for (int j = 0; j < 8; ++j) { const int col = 4 * lane + 256 * j; const f32x4 o = v[j] * rn * cs[j] + sv[j]; u32x2 pq; pq.x = pk2(o.x, o.y); pq.y = pk2(o.z, o.w); *(u32x2*)(dst + (size_t)(row0 + r) * DM + col) = pq; }
	v_pk_mul_f32 v[54:55], v[54:55], v[134:135] op_sel_hi:[1,0]
	v_add3_u32 v52, v52, v56, s72
	v_bfe_u32 v56, v53, 16, 1
	v_pk_fma_f32 v[54:55], v[104:105], v[54:55], v[10:11]
	v_lshrrev_b32_e32 v52, 16, v52
	v_add3_u32 v53, v53, v56, s72
	v_and_or_b32 v52, v53, s73, v52
	v_bfe_u32 v53, v54, 16, 1
	v_add3_u32 v53, v54, v53, s72
	v_bfe_u32 v54, v55, 16, 1
	v_lshrrev_b32_e32 v53, 16, v53
	v_add3_u32 v54, v55, v54, s72
	v_pk_mul_f32 v[48:49], v[48:49], v[134:135] op_sel_hi:[1,0]
	v_and_or_b32 v53, v54, s73, v53
	v_pk_fma_f32 v[48:49], v[110:111], v[48:49], v[12:13]
	global_store_dwordx2 v[62:63], v[52:53], off offset:1024
	v_bfe_u32 v52, v48, 16, 1
	v_pk_mul_f32 v[50:51], v[50:51], v[134:135] op_sel_hi:[1,0]
	v_add3_u32 v48, v48, v52, s72
	v_bfe_u32 v52, v49, 16, 1
	v_pk_fma_f32 v[50:51], v[108:109], v[50:51], v[14:15]
	v_lshrrev_b32_e32 v48, 16, v48
	v_add3_u32 v49, v49, v52, s72
	v_and_or_b32 v48, v49, s73, v48
	v_bfe_u32 v49, v50, 16, 1
	v_add3_u32 v49, v50, v49, s72
	v_bfe_u32 v50, v51, 16, 1
	v_lshrrev_b32_e32 v49, 16, v49
	v_add3_u32 v50, v51, v50, s72
	v_pk_mul_f32 v[44:45], v[44:45], v[134:135] op_sel_hi:[1,0]
	v_and_or_b32 v49, v50, s73, v49
	v_pk_fma_f32 v[44:45], v[114:115], v[44:45], v[16:17]
	global_store_dwordx2 v[62:63], v[48:49], off offset:1536
	v_bfe_u32 v48, v44, 16, 1
	v_pk_mul_f32 v[46:47], v[46:47], v[134:135] op_sel_hi:[1,0]
	v_add3_u32 v44, v44, v48, s72
	v_bfe_u32 v48, v45, 16, 1
	v_pk_fma_f32 v[46:47], v[112:113], v[46:47], v[18:19]
	v_lshrrev_b32_e32 v44, 16, v44
	v_add3_u32 v45, v45, v48, s72
	v_and_or_b32 v44, v45, s73, v44
	v_bfe_u32 v45, v46, 16, 1
	v_add3_u32 v45, v46, v45, s72
	v_bfe_u32 v46, v47, 16, 1
	v_lshrrev_b32_e32 v45, 16, v45
	v_add3_u32 v46, v47, v46, s72
	v_pk_mul_f32 v[40:41], v[40:41], v[134:135] op_sel_hi:[1,0]
	v_and_or_b32 v45, v46, s73, v45
	v_pk_fma_f32 v[40:41], v[118:119], v[40:41], v[20:21]
	global_store_dwordx2 v[62:63], v[44:45], off offset:2048
	v_bfe_u32 v44, v40, 16, 1
	v_pk_mul_f32 v[42:43], v[42:43], v[134:135] op_sel_hi:[1,0]
	v_add3_u32 v40, v40, v44, s72
	v_bfe_u32 v44, v41, 16, 1
	v_pk_fma_f32 v[42:43], v[116:117], v[42:43], v[22:23]
	v_lshrrev_b32_e32 v40, 16, v40
	v_add3_u32 v41, v41, v44, s72
	v_and_or_b32 v40, v41, s73, v40
	v_bfe_u32 v41, v42, 16, 1
	v_add3_u32 v41, v42, v41, s72
	v_bfe_u32 v42, v43, 16, 1
	v_lshrrev_b32_e32 v41, 16, v41
	v_add3_u32 v42, v43, v42, s72
	v_pk_mul_f32 v[36:37], v[36:37], v[134:135] op_sel_hi:[1,0]
	v_and_or_b32 v41, v42, s73, v41
	v_pk_fma_f32 v[36:37], v[122:123], v[36:37], v[24:25]
	global_store_dwordx2 v[62:63], v[40:41], off offset:2560
	v_bfe_u32 v40, v36, 16, 1
	v_pk_mul_f32 v[38:39], v[38:39], v[134:135] op_sel_hi:[1,0]
	v_add3_u32 v36, v36, v40, s72
	v_bfe_u32 v40, v37, 16, 1
	v_pk_fma_f32 v[38:39], v[120:121], v[38:39], v[26:27]
	v_lshrrev_b32_e32 v36, 16, v36
	v_add3_u32 v37, v37, v40, s72
	v_and_or_b32 v36, v37, s73, v36
	v_bfe_u32 v37, v38, 16, 1
	v_add3_u32 v37, v38, v37, s72
	v_bfe_u32 v38, v39, 16, 1
	v_lshrrev_b32_e32 v37, 16, v37
	v_add3_u32 v38, v39, v38, s72
	v_pk_mul_f32 v[32:33], v[32:33], v[134:135] op_sel_hi:[1,0]
	v_and_or_b32 v37, v38, s73, v37
	v_pk_fma_f32 v[32:33], v[126:127], v[32:33], v[28:29]
	global_store_dwordx2 v[62:63], v[36:37], off offset:3072
	v_bfe_u32 v36, v32, 16, 1
	v_pk_mul_f32 v[34:35], v[34:35], v[134:135] op_sel_hi:[1,0]
	v_add3_u32 v32, v32, v36, s72
	v_bfe_u32 v36, v33, 16, 1
	v_pk_fma_f32 v[34:35], v[124:125], v[34:35], v[30:31]
	v_lshrrev_b32_e32 v32, 16, v32
	v_add3_u32 v33, v33, v36, s72
	v_and_or_b32 v32, v33, s73, v32
	v_bfe_u32 v33, v34, 16, 1
	v_add3_u32 v33, v34, v33, s72
	v_bfe_u32 v34, v35, 16, 1
	v_lshrrev_b32_e32 v33, 16, v33
	v_add3_u32 v34, v35, v34, s72
	v_and_or_b32 v33, v34, s73, v33
	global_store_dwordx2 v[62:63], v[32:33], off offset:3584
	global_load_dwordx4 v[60:63], v[132:133], off
	global_load_dwordx4 v[56:59], v[132:133], off offset:1024
	global_load_dwordx4 v[52:55], v[132:133], off offset:2048
	global_load_dwordx4 v[48:51], v[132:133], off offset:3072
	v_add_co_u32_e32 v154, vcc, s33, v130
	s_nop 1
	v_addc_co_u32_e32 v155, vcc, 0, v131, vcc
	global_load_dwordx4 v[44:47], v[154:155], off
	global_load_dwordx4 v[40:43], v[154:155], off offset:1024
	global_load_dwordx4 v[36:39], v[154:155], off offset:2048
	global_load_dwordx4 v[32:35], v[154:155], off offset:3072
	s_nop 0
	v_add_u32_e32 v132, 1, v128
	v_ashrrev_i32_e32 v133, 31, v132
	v_lshlrev_b64 v[132:133], 12, v[132:133]
	v_add_u32_e32 v128, 2, v128
	s_nop 1
	s_waitcnt vmcnt(7)
	v_mul_f32_e32 v150, v61, v61
	v_mul_f32_e32 v151, v63, v63
	v_fmac_f32_e32 v150, v60, v60
	v_fmac_f32_e32 v151, v62, v62
	v_add_f32_e32 v79, v150, v151
	s_waitcnt vmcnt(6)
	v_mul_f32_e32 v150, v57, v57
	v_mul_f32_e32 v151, v59, v59
	v_fmac_f32_e32 v150, v56, v56
	v_fmac_f32_e32 v151, v58, v58
	v_add_f32_e32 v150, v150, v151
	v_add_f32_e32 v79, v79, v150
	s_waitcnt vmcnt(5)
	v_mul_f32_e32 v150, v53, v53
	v_mul_f32_e32 v151, v55, v55
	v_fmac_f32_e32 v150, v52, v52
	v_fmac_f32_e32 v151, v54, v54
	v_add_f32_e32 v150, v150, v151
	v_add_f32_e32 v79, v79, v150
	s_waitcnt vmcnt(4)
	v_mul_f32_e32 v150, v49, v49
	v_mul_f32_e32 v151, v51, v51
	v_fmac_f32_e32 v150, v48, v48
	v_fmac_f32_e32 v151, v50, v50
	v_add_f32_e32 v150, v150, v151
	v_add_f32_e32 v79, v79, v150
	s_waitcnt vmcnt(3)
	v_mul_f32_e32 v150, v45, v45
	v_mul_f32_e32 v151, v47, v47
	v_fmac_f32_e32 v150, v44, v44
	v_fmac_f32_e32 v151, v46, v46
	v_add_f32_e32 v150, v150, v151
	v_add_f32_e32 v79, v79, v150
	s_waitcnt vmcnt(2)
	v_mul_f32_e32 v150, v41, v41
	v_mul_f32_e32 v151, v43, v43
	v_fmac_f32_e32 v150, v40, v40
	v_fmac_f32_e32 v151, v42, v42
	v_add_f32_e32 v150, v150, v151
	v_add_f32_e32 v79, v79, v150
	s_waitcnt vmcnt(1)
; template <int SRC> __device__ __forceinline__ void prenorm_rows(const LArgs& a, int nrows, const float* nw, const float* mods_layer, int shift_part, bf16* dst) {
;     ...
;             for (int j = 0; j < 8; ++j) { v[j] = *(const f32x4*)(src + 4 * lane + 256 * j); ss += (v[j].x * v[j].x + v[j].y * v[j].y) + (v[j].z * v[j].z + v[j].w * v[j].w); }
;             const float rn = 1.f / sqrtf(wave_sum(ss) * (1.f / DM) + 1e-6f);
	v_mul_f32_e32 v150, v37, v37
	v_mul_f32_e32 v151, v39, v39
	v_fmac_f32_e32 v150, v36, v36
	v_fmac_f32_e32 v151, v38, v38
	v_add_f32_e32 v150, v150, v151
	v_add_f32_e32 v79, v79, v150
	s_waitcnt vmcnt(0)
	v_mul_f32_e32 v150, v33, v33
	v_mul_f32_e32 v151, v35, v35
	v_fmac_f32_e32 v150, v32, v32
	v_fmac_f32_e32 v151, v34, v34
	v_add_f32_e32 v150, v150, v151
	v_add_f32_e32 v79, v79, v150
	ds_swizzle_b32 v81, v79 offset:swizzle(SWAP,1)
	s_waitcnt lgkmcnt(0)
	v_add_f32_e32 v79, v79, v81
	ds_swizzle_b32 v81, v79 offset:swizzle(SWAP,2)
	s_waitcnt lgkmcnt(0)
	v_add_f32_e32 v79, v79, v81
	ds_swizzle_b32 v81, v79 offset:swizzle(SWAP,4)
	s_waitcnt lgkmcnt(0)
	v_add_f32_e32 v79, v79, v81
	ds_swizzle_b32 v81, v79 offset:swizzle(SWAP,8)
	s_waitcnt lgkmcnt(0)
	v_add_f32_e32 v79, v79, v81
	ds_swizzle_b32 v81, v79 offset:swizzle(SWAP,16)
	s_waitcnt lgkmcnt(0)
; __device__ __forceinline__ unsigned pk2(float lo, float hi) { return f2bf(lo) | (f2bf(hi) << 16); }
; template <int SRC> __device__ __forceinline__ void prenorm_rows(const LArgs& a, int nrows, const float* nw, const float* mods_layer, int shift_part, bf16* dst) {
;     ...
;     for (int chunk = gw; chunk < nrows / 16; chunk += NGW) {
;     ...
;             const float rn = 1.f / sqrtf(wave_sum(ss) * (1.f / DM) + 1e-6f);
; #pragma unroll
;             for (int j = 0; j < 8; ++j) { const int col = 4 * lane + 256 * j; const f32x4 o = v[j] * rn * cs[j] + sv[j]; u32x2 pq; pq.x = pk2(o.x, o.y); pq.y = pk2(o.z, o.w); *(u32x2*)(dst + (size_t)(row0 + r) * DM + col) = pq; }
;         }
	v_add_f32_e32 v79, v79, v81
	s_nop 0
	v_readlane_b32 s1, v79, 32
	v_readlane_b32 s0, v79, 0
	s_nop 0
	v_mov_b32_e32 v79, s1
	v_add_f32_e32 v79, s0, v79
	v_fmamk_f32 v79, v79, 0x3a000000, v193
	v_cmp_gt_f32_e32 vcc, s61, v79
	v_mul_f32_e32 v81, 0x4f800000, v79
	s_nop 0
	v_cndmask_b32_e32 v79, v79, v81, vcc
	v_sqrt_f32_e32 v81, v79
	s_nop 0
	v_add_u32_e32 v83, -1, v81
	v_fma_f32 v85, -v83, v81, v79
	v_cmp_ge_f32_e64 s[0:1], 0, v85
	v_add_u32_e32 v85, 1, v81
	s_nop 0
	v_cndmask_b32_e64 v83, v81, v83, s[0:1]
	v_fma_f32 v81, -v85, v81, v79
	v_cmp_lt_f32_e64 s[0:1], 0, v81
	s_nop 1
	v_cndmask_b32_e64 v81, v83, v85, s[0:1]
	v_mul_f32_e32 v83, 0x37800000, v81
	v_cndmask_b32_e32 v81, v81, v83, vcc
	v_cmp_class_f32_e32 vcc, v79, v194
	s_nop 1
	v_cndmask_b32_e32 v79, v81, v79, vcc
	v_div_scale_f32 v81, s[0:1], v79, v79, 1.0
	v_rcp_f32_e32 v83, v81
	s_nop 0
	v_fma_f32 v85, -v81, v83, 1.0
	v_fmac_f32_e32 v83, v85, v83
	v_div_scale_f32 v85, vcc, 1.0, v79, 1.0
	v_mul_f32_e32 v87, v85, v83
	v_fma_f32 v89, -v81, v87, v85
	v_fmac_f32_e32 v87, v89, v83
	v_fma_f32 v81, -v81, v87, v85
	v_div_fmas_f32 v81, v81, v83, v87
	v_div_fixup_f32 v130, v81, v79, 1.0
	v_pk_mul_f32 v[60:61], v[60:61], v[130:131] op_sel_hi:[1,0]
	v_pk_mul_f32 v[62:63], v[62:63], v[130:131] op_sel_hi:[1,0]
	v_pk_fma_f32 v[60:61], v[98:99], v[60:61], v[0:1]
	v_pk_fma_f32 v[62:63], v[96:97], v[62:63], v[2:3]
	v_bfe_u32 v79, v60, 16, 1
	v_add3_u32 v60, v60, v79, s72
	v_bfe_u32 v79, v61, 16, 1
	v_lshrrev_b32_e32 v60, 16, v60
	v_add3_u32 v61, v61, v79, s72
	v_and_or_b32 v60, v61, s73, v60
	v_bfe_u32 v61, v62, 16, 1
	v_add3_u32 v61, v62, v61, s72
	v_bfe_u32 v62, v63, 16, 1
	v_lshrrev_b32_e32 v61, 16, v61
	v_add3_u32 v62, v63, v62, s72
	v_pk_mul_f32 v[56:57], v[56:57], v[130:131] op_sel_hi:[1,0]
	v_and_or_b32 v61, v62, s73, v61
	v_lshl_add_u64 v[62:63], v[74:75], 0, v[132:133]
	v_pk_fma_f32 v[56:57], v[102:103], v[56:57], v[4:5]
	global_store_dwordx2 v[62:63], v[60:61], off
	v_bfe_u32 v60, v56, 16, 1
	v_pk_mul_f32 v[58:59], v[58:59], v[130:131] op_sel_hi:[1,0]
	v_add3_u32 v56, v56, v60, s72
	v_bfe_u32 v60, v57, 16, 1
	v_pk_fma_f32 v[58:59], v[100:101], v[58:59], v[6:7]
	v_lshrrev_b32_e32 v56, 16, v56
	v_add3_u32 v57, v57, v60, s72
	v_and_or_b32 v56, v57, s73, v56
	v_bfe_u32 v57, v58, 16, 1
	v_add3_u32 v57, v58, v57, s72
	v_bfe_u32 v58, v59, 16, 1
	v_lshrrev_b32_e32 v57, 16, v57
	v_add3_u32 v58, v59, v58, s72
	v_pk_mul_f32 v[52:53], v[52:53], v[130:131] op_sel_hi:[1,0]
	v_and_or_b32 v57, v58, s73, v57
	v_pk_fma_f32 v[52:53], v[106:107], v[52:53], v[8:9]
	global_store_dwordx2 v[62:63], v[56:57], off offset:512
	v_bfe_u32 v56, v52, 16, 1
	v_pk_mul_f32 v[54:55], v[54:55], v[130:131] op_sel_hi:[1,0]
	v_add3_u32 v52, v52, v56, s72
	v_bfe_u32 v56, v53, 16, 1
	v_pk_fma_f32 v[54:55], v[104:105], v[54:55], v[10:11]
	v_lshrrev_b32_e32 v52, 16, v52
	v_add3_u32 v53, v53, v56, s72
	v_and_or_b32 v52, v53, s73, v52
	v_bfe_u32 v53, v54, 16, 1
	v_add3_u32 v53, v54, v53, s72
	v_bfe_u32 v54, v55, 16, 1
	v_lshrrev_b32_e32 v53, 16, v53
	v_add3_u32 v54, v55, v54, s72
	v_pk_mul_f32 v[48:49], v[48:49], v[130:131] op_sel_hi:[1,0]
	v_and_or_b32 v53, v54, s73, v53
	v_pk_fma_f32 v[48:49], v[110:111], v[48:49], v[12:13]
	global_store_dwordx2 v[62:63], v[52:53], off offset:1024
	v_bfe_u32 v52, v48, 16, 1
	v_pk_mul_f32 v[50:51], v[50:51], v[130:131] op_sel_hi:[1,0]
	v_add3_u32 v48, v48, v52, s72
	v_bfe_u32 v52, v49, 16, 1
	v_pk_fma_f32 v[50:51], v[108:109], v[50:51], v[14:15]
	v_lshrrev_b32_e32 v48, 16, v48
	v_add3_u32 v49, v49, v52, s72
	v_and_or_b32 v48, v49, s73, v48
	v_bfe_u32 v49, v50, 16, 1
	v_add3_u32 v49, v50, v49, s72
	v_bfe_u32 v50, v51, 16, 1
	v_lshrrev_b32_e32 v49, 16, v49
	v_add3_u32 v50, v51, v50, s72
	v_pk_mul_f32 v[44:45], v[44:45], v[130:131] op_sel_hi:[1,0]
	v_and_or_b32 v49, v50, s73, v49
	v_pk_fma_f32 v[44:45], v[114:115], v[44:45], v[16:17]
	global_store_dwordx2 v[62:63], v[48:49], off offset:1536
	v_bfe_u32 v48, v44, 16, 1
	v_pk_mul_f32 v[46:47], v[46:47], v[130:131] op_sel_hi:[1,0]
	v_add3_u32 v44, v44, v48, s72
	v_bfe_u32 v48, v45, 16, 1
	v_pk_fma_f32 v[46:47], v[112:113], v[46:47], v[18:19]
	v_lshrrev_b32_e32 v44, 16, v44
	v_add3_u32 v45, v45, v48, s72
	v_and_or_b32 v44, v45, s73, v44
	v_bfe_u32 v45, v46, 16, 1
	v_add3_u32 v45, v46, v45, s72
	v_bfe_u32 v46, v47, 16, 1
	v_lshrrev_b32_e32 v45, 16, v45
	v_add3_u32 v46, v47, v46, s72
	v_pk_mul_f32 v[40:41], v[40:41], v[130:131] op_sel_hi:[1,0]
	v_and_or_b32 v45, v46, s73, v45
	v_pk_fma_f32 v[40:41], v[118:119], v[40:41], v[20:21]
	global_store_dwordx2 v[62:63], v[44:45], off offset:2048
	v_bfe_u32 v44, v40, 16, 1
	v_pk_mul_f32 v[42:43], v[42:43], v[130:131] op_sel_hi:[1,0]
	v_add3_u32 v40, v40, v44, s72
	v_bfe_u32 v44, v41, 16, 1
	v_pk_fma_f32 v[42:43], v[116:117], v[42:43], v[22:23]
	v_lshrrev_b32_e32 v40, 16, v40
	v_add3_u32 v41, v41, v44, s72
	v_and_or_b32 v40, v41, s73, v40
	v_bfe_u32 v41, v42, 16, 1
	v_add3_u32 v41, v42, v41, s72
	v_bfe_u32 v42, v43, 16, 1
	v_lshrrev_b32_e32 v41, 16, v41
	v_add3_u32 v42, v43, v42, s72
	v_pk_mul_f32 v[36:37], v[36:37], v[130:131] op_sel_hi:[1,0]
	v_and_or_b32 v41, v42, s73, v41
	v_pk_fma_f32 v[36:37], v[122:123], v[36:37], v[24:25]
	global_store_dwordx2 v[62:63], v[40:41], off offset:2560
	v_bfe_u32 v40, v36, 16, 1
	v_pk_mul_f32 v[38:39], v[38:39], v[130:131] op_sel_hi:[1,0]
	v_add3_u32 v36, v36, v40, s72
	v_bfe_u32 v40, v37, 16, 1
	v_pk_fma_f32 v[38:39], v[120:121], v[38:39], v[26:27]
	v_lshrrev_b32_e32 v36, 16, v36
	v_add3_u32 v37, v37, v40, s72
	v_and_or_b32 v36, v37, s73, v36
	v_bfe_u32 v37, v38, 16, 1
	v_add3_u32 v37, v38, v37, s72
	v_bfe_u32 v38, v39, 16, 1
	v_lshrrev_b32_e32 v37, 16, v37
	v_add3_u32 v38, v39, v38, s72
	v_pk_mul_f32 v[32:33], v[32:33], v[130:131] op_sel_hi:[1,0]
	v_and_or_b32 v37, v38, s73, v37
	v_pk_fma_f32 v[32:33], v[126:127], v[32:33], v[28:29]
	global_store_dwordx2 v[62:63], v[36:37], off offset:3072
	v_bfe_u32 v36, v32, 16, 1
	v_pk_mul_f32 v[34:35], v[34:35], v[130:131] op_sel_hi:[1,0]
	v_add3_u32 v32, v32, v36, s72
	v_bfe_u32 v36, v33, 16, 1
	v_pk_fma_f32 v[34:35], v[124:125], v[34:35], v[30:31]
	v_lshrrev_b32_e32 v32, 16, v32
	v_add3_u32 v33, v33, v36, s72
	v_and_or_b32 v32, v33, s73, v32
	v_bfe_u32 v33, v34, 16, 1
	v_add3_u32 v33, v34, v33, s72
	v_bfe_u32 v34, v35, 16, 1
	v_lshrrev_b32_e32 v33, 16, v33
	v_add3_u32 v34, v35, v34, s72
	v_and_or_b32 v33, v34, s73, v33
	global_store_dwordx2 v[62:63], v[32:33], off offset:3584
	s_cbranch_scc0 .LBB0_269
	v_add_u32_e32 v135, s86, v135
	v_cmp_lt_i32_e32 vcc, s82, v135
	v_readlane_b32 s0, v254, 6
	s_or_b64 s[10:11], vcc, s[10:11]
	s_nop 0
	v_add_u32_e32 v78, s0, v78
	s_andn2_b64 exec, exec, s[10:11]
	s_cbranch_execnz .LBB0_268

; __device__ __forceinline__ unsigned cvt_pk_bf16(float lo, float hi) { unsigned r; asm volatile("v_cvt_pk_bf16_f32 %0, %1, %2" : "=v"(r) : "v"(lo), "v"(hi)); return r; }
; #define LAS __attribute__((address_space(3)))
; __device__ __forceinline__ float xor32_get(float v, int xaddr) { return __builtin_bit_cast(float, __builtin_amdgcn_ds_bpermute(xaddr, __builtin_bit_cast(int, v))); }
; __device__ __forceinline__ void attn_phase(const LArgs& a, LAS unsigned char* lds) {
;     ...
;             for (int kb = 0; kb < 2; ++kb) {
; #pragma unroll
;                 for (int r = 0; r < 16; ++r) s[kb][r] = 0.f;
; #pragma unroll
;                 for (int ks = 0; ks < 4; ++ks) { const bf16x8 kf = *(const LAS bf16x8*)(kb_ + (32 * kb + kappa) * KROW + mp * 128 + ks * 32 + hi * 16);
;                     s[kb] = __builtin_amdgcn_mfma_f32_32x32x16_bf16(kf, qf[ks], s[kb], 0, 0, 0); }
;             }
;             if (!late) ATT_PV_PRE(vcur);
;             float mx = s[0][0];
; #pragma unroll
;             for (int r = 1; r < 16; ++r) mx = fmaxf(mx, s[0][r]);
; #pragma unroll
;             for (int r = 0; r < 16; ++r) mx = fmaxf(mx, s[1][r]);
;             mx = fmaxf(mx, xor32_get(mx, xaddr));
;             const float mnew = fmaxf(mrun, mx);
;             if (__any(mnew > mrun)) {
;                 const float alpha = __builtin_amdgcn_exp2f(mrun - mnew); lrun *= alpha;
; #pragma unroll
;                 for (int d = 0; d < 4; ++d)
; #pragma unroll
;                     for (int r = 0; r < 16; ++r) o[d][r] *= alpha;
;                 mrun = mnew;
;             }
;             float psum = 0.f;
; #pragma unroll
;             for (int kb = 0; kb < 2; ++kb)
; #pragma unroll
;                 for (int r = 0; r < 16; ++r) { const float pv = __builtin_amdgcn_exp2f(s[kb][r] - mrun); s[kb][r] = pv; psum += pv; }
;             lrun += psum;
; #pragma unroll
;             for (int kb = 0; kb < 2; ++kb)
; #pragma unroll
;                 for (int g = 0; g < 2; ++g) {
;                     u32x4 w4; w4.x = pg8::cvt_pk_bf16(s[kb][8 * g + 0], s[kb][8 * g + 1]); w4.y = pg8::cvt_pk_bf16(s[kb][8 * g + 2], s[kb][8 * g + 3]);
;                     w4.z = pg8::cvt_pk_bf16(s[kb][8 * g + 4], s[kb][8 * g + 5]); w4.w = pg8::cvt_pk_bf16(s[kb][8 * g + 6], s[kb][8 * g + 7]);
;                     pw[2 * kb + g] = w4;
;                 }
.Lattn_noload:
	s_and_b32 s23, s21, 1
	s_mul_i32 s16, s23, 0x4400
	s_mul_i32 s24, s22, 0x4800
	v_add_u32_e32 v252, s16, v171
	v_add3_u32 v218, s24, v148, v178
	ds_read_b128 v[96:99], v252
	ds_read_b128 v[100:103], v252 offset:32
	ds_read_b128 v[104:107], v252 offset:64
	ds_read_b128 v[108:111], v252 offset:96
	ds_read_b128 v[182:185], v252 offset:8704
	ds_read_b128 v[186:189], v252 offset:8736
	ds_read_b128 v[224:227], v252 offset:8768
	ds_read_b128 v[244:247], v252 offset:8800
	ds_read_b128 v[174:177], v218 offset:34816
	ds_read_b128 v[248:251], v218 offset:39424
	s_waitcnt lgkmcnt(9)
	v_mfma_f32_32x32x16_bf16 v[228:243], v[96:99], v[112:115], v[202:217]
	ds_read_b128 v[96:99], v218 offset:44032
	s_waitcnt lgkmcnt(9)
	v_mfma_f32_32x32x16_bf16 v[228:243], v[100:103], v[116:119], v[228:243]
	ds_read_b128 v[100:103], v218 offset:48640
	s_waitcnt lgkmcnt(9)
	v_mfma_f32_32x32x16_bf16 v[228:243], v[104:107], v[120:123], v[228:243]
	ds_read_b128 v[104:107], v218 offset:34848
	s_waitcnt lgkmcnt(9)
	v_mfma_f32_32x32x16_bf16 v[228:243], v[108:111], v[124:127], v[228:243]
	ds_read_b128 v[108:111], v218 offset:39456
	s_waitcnt lgkmcnt(9)
	v_mfma_f32_32x32x16_bf16 v[64:79], v[182:185], v[112:115], v[202:217]
	ds_read_b128 v[182:185], v218 offset:44064
	s_waitcnt lgkmcnt(9)
	v_mfma_f32_32x32x16_bf16 v[64:79], v[186:189], v[116:119], v[64:79]
	ds_read_b128 v[186:189], v218 offset:48672
	s_waitcnt lgkmcnt(9)
	v_mfma_f32_32x32x16_bf16 v[64:79], v[224:227], v[120:123], v[64:79]
	ds_read_b128 v[224:227], v218 offset:34880
	s_waitcnt lgkmcnt(9)
	v_mfma_f32_32x32x16_bf16 v[64:79], v[244:247], v[124:127], v[64:79]
	ds_read_b128 v[244:247], v218 offset:39488
	s_waitcnt lgkmcnt(9)
	v_mfma_f32_32x32x16_bf16 v[48:63], v[174:177], v[92:95], v[48:63]
	ds_read_b128 v[174:177], v218 offset:44096
	v_exp_f32_e32 v228, v228
	v_exp_f32_e32 v229, v229
	v_exp_f32_e32 v230, v230
	s_waitcnt lgkmcnt(9)
	v_mfma_f32_32x32x16_bf16 v[32:47], v[248:251], v[92:95], v[32:47]
	ds_read_b128 v[248:251], v218 offset:48704
	v_exp_f32_e32 v231, v231
	v_exp_f32_e32 v232, v232
	v_exp_f32_e32 v233, v233
	s_waitcnt lgkmcnt(9)
	v_mfma_f32_32x32x16_bf16 v[16:31], v[96:99], v[92:95], v[16:31]
	ds_read_b128 v[96:99], v218 offset:34912
	v_exp_f32_e32 v234, v234
	v_exp_f32_e32 v235, v235
	v_exp_f32_e32 v236, v236
	s_waitcnt lgkmcnt(9)
	v_mfma_f32_32x32x16_bf16 v[0:15], v[100:103], v[92:95], v[0:15]
	ds_read_b128 v[100:103], v218 offset:39520
	v_exp_f32_e32 v237, v237
	v_exp_f32_e32 v238, v238
	v_exp_f32_e32 v239, v239
	s_waitcnt lgkmcnt(9)
	v_mfma_f32_32x32x16_bf16 v[48:63], v[104:107], v[88:91], v[48:63]
	ds_read_b128 v[104:107], v218 offset:44128
	v_exp_f32_e32 v240, v240
	v_exp_f32_e32 v241, v241
	v_exp_f32_e32 v242, v242
	s_waitcnt lgkmcnt(9)
	v_mfma_f32_32x32x16_bf16 v[32:47], v[108:111], v[88:91], v[32:47]
	ds_read_b128 v[108:111], v218 offset:48736
	v_exp_f32_e32 v243, v243
	v_exp_f32_e32 v64, v64
	v_add_f32_e32 v190, v228, v229
	v_add_f32_e32 v190, v190, v230
	s_waitcnt lgkmcnt(9)
	v_mfma_f32_32x32x16_bf16 v[16:31], v[182:185], v[88:91], v[16:31]
	v_exp_f32_e32 v65, v65
	v_add_f32_e32 v190, v190, v231
	v_add_f32_e32 v190, v190, v232
	v_exp_f32_e32 v66, v66
	v_add_f32_e32 v190, v190, v233
	s_waitcnt lgkmcnt(8)
	v_mfma_f32_32x32x16_bf16 v[0:15], v[186:189], v[88:91], v[0:15]
	v_add_f32_e32 v190, v190, v234
	v_exp_f32_e32 v67, v67
	v_add_f32_e32 v190, v190, v235
	v_add_f32_e32 v190, v190, v236
	v_exp_f32_e32 v68, v68
	s_andn2_b64 vcc, exec, s[0:1]
	s_cbranch_vccnz .Lattn_nowrite
	s_xor_b32 s0, s23, 1
	s_mulk_i32 s0, 0x4400
	s_mul_i32 s1, s20, 0x4800
	v_add_u32_e32 v219, s0, v168
	s_waitcnt vmcnt(3)
	ds_write_b128 v219, v[128:131]
	s_waitcnt vmcnt(2)
	ds_write_b128 v219, v[132:135] offset:8704
	v_add_u32_e32 v219, s1, v169
	s_waitcnt vmcnt(1)
	ds_write_b128 v219, v[136:139] offset:34816
	s_waitcnt vmcnt(0)
	ds_write_b128 v219, v[140:143] offset:44032
.Lattn_nowrite:
	s_waitcnt lgkmcnt(7)
	v_mfma_f32_32x32x16_bf16 v[48:63], v[224:227], v[84:87], v[48:63]
	v_add_f32_e32 v190, v190, v237
	v_add_f32_e32 v190, v190, v238
	v_exp_f32_e32 v69, v69
	v_add_f32_e32 v190, v190, v239
	v_add_f32_e32 v190, v190, v240
	s_waitcnt lgkmcnt(6)
	v_mfma_f32_32x32x16_bf16 v[32:47], v[244:247], v[84:87], v[32:47]
	v_exp_f32_e32 v70, v70
	v_add_f32_e32 v190, v190, v241
	v_add_f32_e32 v190, v190, v242
	v_exp_f32_e32 v71, v71
	v_add_f32_e32 v190, v190, v243
	s_waitcnt lgkmcnt(5)
	v_mfma_f32_32x32x16_bf16 v[16:31], v[174:177], v[84:87], v[16:31]
	v_exp_f32_e32 v72, v72
	v_exp_f32_e32 v73, v73
	v_exp_f32_e32 v74, v74
	s_waitcnt lgkmcnt(4)
	v_mfma_f32_32x32x16_bf16 v[0:15], v[248:251], v[84:87], v[0:15]
	v_exp_f32_e32 v75, v75
	v_exp_f32_e32 v76, v76
	v_exp_f32_e32 v77, v77
	s_waitcnt lgkmcnt(3)
	v_mfma_f32_32x32x16_bf16 v[48:63], v[96:99], v[80:83], v[48:63]
	v_exp_f32_e32 v78, v78
	v_exp_f32_e32 v79, v79
	v_cvt_pk_bf16_f32 v92, v228, v229
	v_cvt_pk_bf16_f32 v93, v230, v231
	v_cvt_pk_bf16_f32 v94, v232, v233
	s_waitcnt lgkmcnt(2)
	v_mfma_f32_32x32x16_bf16 v[32:47], v[100:103], v[80:83], v[32:47]
	v_cvt_pk_bf16_f32 v95, v234, v235
	v_cvt_pk_bf16_f32 v88, v236, v237
	v_cvt_pk_bf16_f32 v89, v238, v239
	v_cvt_pk_bf16_f32 v90, v240, v241
	v_cvt_pk_bf16_f32 v91, v242, v243
	v_add_f32_e32 v191, v64, v65
	v_add_f32_e32 v191, v191, v66
	s_waitcnt lgkmcnt(1)
	v_mfma_f32_32x32x16_bf16 v[16:31], v[104:107], v[80:83], v[16:31]
	v_add_f32_e32 v191, v191, v67
	v_add_f32_e32 v191, v191, v68
	v_add_f32_e32 v191, v191, v69
	v_add_f32_e32 v191, v191, v70
	v_add_f32_e32 v191, v191, v71
	v_add_f32_e32 v191, v191, v72
	v_add_f32_e32 v191, v191, v73
	s_waitcnt lgkmcnt(0)
	v_mfma_f32_32x32x16_bf16 v[0:15], v[108:111], v[80:83], v[0:15]
	v_add_f32_e32 v191, v191, v74
	v_add_f32_e32 v191, v191, v75
	v_add_f32_e32 v191, v191, v76
	v_add_f32_e32 v191, v191, v77
	v_add_f32_e32 v191, v191, v78
	v_add_f32_e32 v191, v191, v79
	v_add_f32_e32 v190, v190, v191
	v_cvt_pk_bf16_f32 v84, v64, v65
	v_cvt_pk_bf16_f32 v85, v66, v67
	v_cvt_pk_bf16_f32 v86, v68, v69
	v_cvt_pk_bf16_f32 v87, v70, v71
	v_cvt_pk_bf16_f32 v80, v72, v73
	v_cvt_pk_bf16_f32 v81, v74, v75
	v_cvt_pk_bf16_f32 v82, v76, v77
	v_cvt_pk_bf16_f32 v83, v78, v79
	v_cmp_lt_f32_e32 vcc, 0x43800000, v190
	s_cbranch_vccnz .Lattn_rare
	v_add_f32_e32 v149, v149, v190

; template <int SRC> __device__ __forceinline__ void prenorm_rows(const LArgs& a, int nrows, const float* nw, const float* mods_layer, int shift_part, bf16* dst) {
;     ...
;         for (int r = 0; r < 16; ++r) {
;             const float* src = src0 + (size_t)r * DM; f32x4 v[8]; float ss = 0.f;
; #pragma unroll
;             for (int j = 0; j < 8; ++j) { v[j] = *(const f32x4*)(src + 4 * lane + 256 * j); ss += (v[j].x * v[j].x + v[j].y * v[j].y) + (v[j].z * v[j].z + v[j].w * v[j].w); }
;             const float rn = 1.f / sqrtf(wave_sum(ss) * (1.f / DM) + 1e-6f);
.LBB0_464:
	v_lshl_add_u64 v[126:127], v[122:123], 0, s[8:9]
	v_ashrrev_i32_e32 v125, 31, v124
	v_lshlrev_b64 v[134:135], 12, v[124:125]
	s_add_u32 s8, s8, 0x4000
	s_addc_u32 s9, s9, 0
	s_cmp_eq_u32 s8, 0x20000
	s_nop 1
	v_add_co_u32_e32 v128, vcc, s47, v126
	s_nop 1
	s_nop 0
	v_addc_co_u32_e32 v129, vcc, 0, v127, vcc
	v_add_co_u32_e32 v152, vcc, s40, v126
	s_nop 1
	v_addc_co_u32_e32 v153, vcc, 0, v127, vcc
	global_load_dwordx4 v[60:63], v[126:127], off
	global_load_dwordx4 v[56:59], v[126:127], off offset:1024
	global_load_dwordx4 v[52:55], v[126:127], off offset:2048
	global_load_dwordx4 v[48:51], v[126:127], off offset:3072
	global_load_dwordx4 v[44:47], v[152:153], off
	global_load_dwordx4 v[40:43], v[152:153], off offset:1024
	global_load_dwordx4 v[36:39], v[152:153], off offset:2048
	global_load_dwordx4 v[32:35], v[152:153], off offset:3072
	s_waitcnt vmcnt(7)
	v_mul_f32_e32 v150, v61, v61
	v_mul_f32_e32 v151, v63, v63
	v_fmac_f32_e32 v150, v60, v60
	v_fmac_f32_e32 v151, v62, v62
	v_add_f32_e32 v77, v150, v151
	s_waitcnt vmcnt(6)
	v_mul_f32_e32 v150, v57, v57
	v_mul_f32_e32 v151, v59, v59
	v_fmac_f32_e32 v150, v56, v56
	v_fmac_f32_e32 v151, v58, v58
	v_add_f32_e32 v150, v150, v151
	v_add_f32_e32 v77, v77, v150
	s_waitcnt vmcnt(5)
	v_mul_f32_e32 v150, v53, v53
	v_mul_f32_e32 v151, v55, v55
	v_fmac_f32_e32 v150, v52, v52
	v_fmac_f32_e32 v151, v54, v54
	v_add_f32_e32 v150, v150, v151
	v_add_f32_e32 v77, v77, v150
	s_waitcnt vmcnt(4)
	v_mul_f32_e32 v150, v49, v49
	v_mul_f32_e32 v151, v51, v51
	v_fmac_f32_e32 v150, v48, v48
	v_fmac_f32_e32 v151, v50, v50
	v_add_f32_e32 v150, v150, v151
	v_add_f32_e32 v77, v77, v150
	s_waitcnt vmcnt(3)
	v_mul_f32_e32 v150, v45, v45
	v_mul_f32_e32 v151, v47, v47
	v_fmac_f32_e32 v150, v44, v44
	v_fmac_f32_e32 v151, v46, v46
	v_add_f32_e32 v150, v150, v151
	v_add_f32_e32 v77, v77, v150
	s_waitcnt vmcnt(2)
	v_mul_f32_e32 v150, v41, v41
	v_mul_f32_e32 v151, v43, v43
	v_fmac_f32_e32 v150, v40, v40
	v_fmac_f32_e32 v151, v42, v42
	v_add_f32_e32 v150, v150, v151
	v_add_f32_e32 v77, v77, v150
	s_waitcnt vmcnt(1)
	v_mul_f32_e32 v150, v37, v37
	v_mul_f32_e32 v151, v39, v39
	v_fmac_f32_e32 v150, v36, v36
	v_fmac_f32_e32 v151, v38, v38
	v_add_f32_e32 v150, v150, v151
	v_add_f32_e32 v77, v77, v150
	s_waitcnt vmcnt(0)
	v_mul_f32_e32 v150, v33, v33
	v_mul_f32_e32 v151, v35, v35
	v_fmac_f32_e32 v150, v32, v32
	v_fmac_f32_e32 v151, v34, v34
	v_add_f32_e32 v150, v150, v151
	v_add_f32_e32 v77, v77, v150
	ds_swizzle_b32 v79, v77 offset:swizzle(SWAP,1)
	s_waitcnt lgkmcnt(0)
	v_add_f32_e32 v77, v77, v79
	ds_swizzle_b32 v79, v77 offset:swizzle(SWAP,2)
	s_waitcnt lgkmcnt(0)
	v_add_f32_e32 v77, v77, v79
	ds_swizzle_b32 v79, v77 offset:swizzle(SWAP,4)
	s_waitcnt lgkmcnt(0)
	v_add_f32_e32 v77, v77, v79
	ds_swizzle_b32 v79, v77 offset:swizzle(SWAP,8)
	s_waitcnt lgkmcnt(0)
	v_add_f32_e32 v77, v77, v79
	ds_swizzle_b32 v79, v77 offset:swizzle(SWAP,16)
	s_waitcnt lgkmcnt(0)
	v_add_f32_e32 v77, v77, v79
	s_nop 0
	v_readlane_b32 s1, v77, 32
	v_readlane_b32 s0, v77, 0
	s_nop 0
	v_mov_b32_e32 v77, s1
	v_add_f32_e32 v77, s0, v77
	v_fmamk_f32 v77, v77, 0x3a000000, v193
	v_cmp_gt_f32_e32 vcc, s61, v77
	v_mul_f32_e32 v79, 0x4f800000, v77
	s_nop 0
	v_cndmask_b32_e32 v77, v77, v79, vcc
	v_sqrt_f32_e32 v79, v77
	s_nop 0
	v_add_u32_e32 v81, -1, v79
	v_fma_f32 v83, -v81, v79, v77
	v_cmp_ge_f32_e64 s[0:1], 0, v83
	v_add_u32_e32 v83, 1, v79
	s_nop 0
	v_cndmask_b32_e64 v81, v79, v81, s[0:1]
	v_fma_f32 v79, -v83, v79, v77
	v_cmp_lt_f32_e64 s[0:1], 0, v79
	s_nop 1
	v_cndmask_b32_e64 v79, v81, v83, s[0:1]
	v_mul_f32_e32 v81, 0x37800000, v79
	v_cndmask_b32_e32 v79, v79, v81, vcc
	v_cmp_class_f32_e32 vcc, v77, v194
	s_nop 1
	v_cndmask_b32_e32 v77, v79, v77, vcc
	v_div_scale_f32 v79, s[0:1], v77, v77, 1.0
	v_rcp_f32_e32 v81, v79
	s_nop 0
	v_fma_f32 v83, -v79, v81, 1.0
	v_fmac_f32_e32 v81, v83, v81
	v_div_scale_f32 v83, vcc, 1.0, v77, 1.0
	v_mul_f32_e32 v85, v83, v81
	v_fma_f32 v87, -v79, v85, v83
	v_fmac_f32_e32 v85, v87, v81
	v_fma_f32 v79, -v79, v85, v83
	v_div_fmas_f32 v79, v79, v81, v85
	v_div_fixup_f32 v130, v79, v77, 1.0
	v_pk_mul_f32 v[60:61], v[60:61], v[130:131] op_sel_hi:[1,0]
	v_pk_mul_f32 v[62:63], v[62:63], v[130:131] op_sel_hi:[1,0]
	v_pk_fma_f32 v[60:61], v[92:93], v[60:61], v[0:1]
	v_pk_fma_f32 v[62:63], v[90:91], v[62:63], v[2:3]
	v_bfe_u32 v77, v60, 16, 1
	v_add3_u32 v60, v60, v77, s72
	v_bfe_u32 v77, v61, 16, 1
	v_lshrrev_b32_e32 v60, 16, v60
	v_add3_u32 v61, v61, v77, s72
	v_and_or_b32 v60, v61, s73, v60
	v_bfe_u32 v61, v62, 16, 1
	v_add3_u32 v61, v62, v61, s72
	v_bfe_u32 v62, v63, 16, 1
	v_lshrrev_b32_e32 v61, 16, v61
	v_add3_u32 v62, v63, v62, s72
	v_pk_mul_f32 v[56:57], v[56:57], v[130:131] op_sel_hi:[1,0]
	v_and_or_b32 v61, v62, s73, v61
	v_lshl_add_u64 v[62:63], v[74:75], 0, v[134:135]
	v_pk_fma_f32 v[56:57], v[96:97], v[56:57], v[4:5]
	global_store_dwordx2 v[62:63], v[60:61], off
	v_bfe_u32 v60, v56, 16, 1
	v_pk_mul_f32 v[58:59], v[58:59], v[130:131] op_sel_hi:[1,0]
	v_add3_u32 v56, v56, v60, s72
	v_bfe_u32 v60, v57, 16, 1
	v_pk_fma_f32 v[58:59], v[94:95], v[58:59], v[6:7]
	v_lshrrev_b32_e32 v56, 16, v56
	v_add3_u32 v57, v57, v60, s72
	v_and_or_b32 v56, v57, s73, v56
	v_bfe_u32 v57, v58, 16, 1
	v_add3_u32 v57, v58, v57, s72
	v_bfe_u32 v58, v59, 16, 1
	v_lshrrev_b32_e32 v57, 16, v57
	v_add3_u32 v58, v59, v58, s72
	v_pk_mul_f32 v[52:53], v[52:53], v[130:131] op_sel_hi:[1,0]
	v_and_or_b32 v57, v58, s73, v57
	v_pk_fma_f32 v[52:53], v[100:101], v[52:53], v[8:9]
	global_store_dwordx2 v[62:63], v[56:57], off offset:512
	v_bfe_u32 v56, v52, 16, 1
	v_pk_mul_f32 v[54:55], v[54:55], v[130:131] op_sel_hi:[1,0]
	v_add3_u32 v52, v52, v56, s72
; __device__ __forceinline__ unsigned pk2(float lo, float hi) { return f2bf(lo) | (f2bf(hi) << 16); }
; template <int SRC> __device__ __forceinline__ void prenorm_rows(const LArgs& a, int nrows, const float* nw, const float* mods_layer, int shift_part, bf16* dst) {
;     ...
;         for (int r = 0; r < 16; ++r) {
;             const float* src = src0 + (size_t)r * DM; f32x4 v[8]; float ss = 0.f;
; #pragma unroll
;             for (int j = 0; j < 8; ++j) { v[j] = *(const f32x4*)(src + 4 * lane + 256 * j); ss += (v[j].x * v[j].x + v[j].y * v[j].y) + (v[j].z * v[j].z + v[j].w * v[j].w); }
;     ...
; #pragma unroll
;             for (int j = 0; j < 8; ++j) { const int col = 4 * lane + 256 * j; const f32x4 o = v[j] * rn * cs[j] + sv[j]; u32x2 pq; pq.x = pk2(o.x, o.y); pq.y = pk2(o.z, o.w); *(u32x2*)(dst + (size_t)(row0 + r) * DM + col) = pq; }
	v_bfe_u32 v56, v53, 16, 1
	v_pk_fma_f32 v[54:55], v[98:99], v[54:55], v[10:11]
	v_lshrrev_b32_e32 v52, 16, v52
	v_add3_u32 v53, v53, v56, s72
	v_and_or_b32 v52, v53, s73, v52
	v_bfe_u32 v53, v54, 16, 1
	v_add3_u32 v53, v54, v53, s72
	v_bfe_u32 v54, v55, 16, 1
	v_lshrrev_b32_e32 v53, 16, v53
	v_add3_u32 v54, v55, v54, s72
	v_pk_mul_f32 v[48:49], v[48:49], v[130:131] op_sel_hi:[1,0]
	v_and_or_b32 v53, v54, s73, v53
	v_pk_fma_f32 v[48:49], v[104:105], v[48:49], v[12:13]
	global_store_dwordx2 v[62:63], v[52:53], off offset:1024
	v_bfe_u32 v52, v48, 16, 1
	v_pk_mul_f32 v[50:51], v[50:51], v[130:131] op_sel_hi:[1,0]
	v_add3_u32 v48, v48, v52, s72
	v_bfe_u32 v52, v49, 16, 1
	v_pk_fma_f32 v[50:51], v[102:103], v[50:51], v[14:15]
	v_lshrrev_b32_e32 v48, 16, v48
	v_add3_u32 v49, v49, v52, s72
	v_and_or_b32 v48, v49, s73, v48
	v_bfe_u32 v49, v50, 16, 1
	v_add3_u32 v49, v50, v49, s72
	v_bfe_u32 v50, v51, 16, 1
	v_lshrrev_b32_e32 v49, 16, v49
	v_add3_u32 v50, v51, v50, s72
	v_pk_mul_f32 v[44:45], v[44:45], v[130:131] op_sel_hi:[1,0]
	v_and_or_b32 v49, v50, s73, v49
	v_pk_fma_f32 v[44:45], v[108:109], v[44:45], v[16:17]
	global_store_dwordx2 v[62:63], v[48:49], off offset:1536
	v_bfe_u32 v48, v44, 16, 1
	v_pk_mul_f32 v[46:47], v[46:47], v[130:131] op_sel_hi:[1,0]
	v_add3_u32 v44, v44, v48, s72
	v_bfe_u32 v48, v45, 16, 1
	v_pk_fma_f32 v[46:47], v[106:107], v[46:47], v[18:19]
	v_lshrrev_b32_e32 v44, 16, v44
	v_add3_u32 v45, v45, v48, s72
	v_and_or_b32 v44, v45, s73, v44
	v_bfe_u32 v45, v46, 16, 1
	v_add3_u32 v45, v46, v45, s72
	v_bfe_u32 v46, v47, 16, 1
	v_lshrrev_b32_e32 v45, 16, v45
	v_add3_u32 v46, v47, v46, s72
	v_pk_mul_f32 v[40:41], v[40:41], v[130:131] op_sel_hi:[1,0]
	v_and_or_b32 v45, v46, s73, v45
	v_pk_fma_f32 v[40:41], v[112:113], v[40:41], v[20:21]
	global_store_dwordx2 v[62:63], v[44:45], off offset:2048
	v_bfe_u32 v44, v40, 16, 1
	v_pk_mul_f32 v[42:43], v[42:43], v[130:131] op_sel_hi:[1,0]
	v_add3_u32 v40, v40, v44, s72
	v_bfe_u32 v44, v41, 16, 1
	v_pk_fma_f32 v[42:43], v[110:111], v[42:43], v[22:23]
	v_lshrrev_b32_e32 v40, 16, v40
	v_add3_u32 v41, v41, v44, s72
	v_and_or_b32 v40, v41, s73, v40
	v_bfe_u32 v41, v42, 16, 1
	v_add3_u32 v41, v42, v41, s72
	v_bfe_u32 v42, v43, 16, 1
	v_lshrrev_b32_e32 v41, 16, v41
	v_add3_u32 v42, v43, v42, s72
	v_pk_mul_f32 v[36:37], v[36:37], v[130:131] op_sel_hi:[1,0]
	v_and_or_b32 v41, v42, s73, v41
	v_pk_fma_f32 v[36:37], v[116:117], v[36:37], v[24:25]
	global_store_dwordx2 v[62:63], v[40:41], off offset:2560
	v_bfe_u32 v40, v36, 16, 1
	v_pk_mul_f32 v[38:39], v[38:39], v[130:131] op_sel_hi:[1,0]
	v_add3_u32 v36, v36, v40, s72
	v_bfe_u32 v40, v37, 16, 1
	v_pk_fma_f32 v[38:39], v[114:115], v[38:39], v[26:27]
	v_lshrrev_b32_e32 v36, 16, v36
	v_add3_u32 v37, v37, v40, s72
	v_and_or_b32 v36, v37, s73, v36
	v_bfe_u32 v37, v38, 16, 1
	v_add3_u32 v37, v38, v37, s72
	v_bfe_u32 v38, v39, 16, 1
	v_lshrrev_b32_e32 v37, 16, v37
	v_add3_u32 v38, v39, v38, s72
	v_pk_mul_f32 v[32:33], v[32:33], v[130:131] op_sel_hi:[1,0]
	v_and_or_b32 v37, v38, s73, v37
	v_pk_fma_f32 v[32:33], v[120:121], v[32:33], v[28:29]
	global_store_dwordx2 v[62:63], v[36:37], off offset:3072
	v_bfe_u32 v36, v32, 16, 1
	v_pk_mul_f32 v[34:35], v[34:35], v[130:131] op_sel_hi:[1,0]
	v_add3_u32 v32, v32, v36, s72
	v_bfe_u32 v36, v33, 16, 1
	v_pk_fma_f32 v[34:35], v[118:119], v[34:35], v[30:31]
	v_lshrrev_b32_e32 v32, 16, v32
	v_add3_u32 v33, v33, v36, s72
	v_and_or_b32 v32, v33, s73, v32
	v_bfe_u32 v33, v34, 16, 1
	v_add3_u32 v33, v34, v33, s72
	v_bfe_u32 v34, v35, 16, 1
	v_lshrrev_b32_e32 v33, 16, v33
	v_add3_u32 v34, v35, v34, s72
	v_and_or_b32 v33, v34, s73, v33
	global_store_dwordx2 v[62:63], v[32:33], off offset:3584
	global_load_dwordx4 v[60:63], v[128:129], off
	global_load_dwordx4 v[56:59], v[128:129], off offset:1024
	global_load_dwordx4 v[52:55], v[128:129], off offset:2048
	global_load_dwordx4 v[48:51], v[128:129], off offset:3072
	v_add_co_u32_e32 v154, vcc, s10, v126
	s_nop 1
	v_addc_co_u32_e32 v155, vcc, 0, v127, vcc
	global_load_dwordx4 v[44:47], v[154:155], off
	global_load_dwordx4 v[40:43], v[154:155], off offset:1024
	global_load_dwordx4 v[36:39], v[154:155], off offset:2048
	global_load_dwordx4 v[32:35], v[154:155], off offset:3072
	s_nop 0
	v_add_u32_e32 v128, 1, v124
	v_ashrrev_i32_e32 v129, 31, v128
	v_lshlrev_b64 v[128:129], 12, v[128:129]
	v_add_u32_e32 v124, 2, v124
	s_nop 1
	s_waitcnt vmcnt(7)
	v_mul_f32_e32 v150, v61, v61
	v_mul_f32_e32 v151, v63, v63
	v_fmac_f32_e32 v150, v60, v60
	v_fmac_f32_e32 v151, v62, v62
	v_add_f32_e32 v77, v150, v151
	s_waitcnt vmcnt(6)
	v_mul_f32_e32 v150, v57, v57
	v_mul_f32_e32 v151, v59, v59
	v_fmac_f32_e32 v150, v56, v56
	v_fmac_f32_e32 v151, v58, v58
	v_add_f32_e32 v150, v150, v151
	v_add_f32_e32 v77, v77, v150
	s_waitcnt vmcnt(5)
	v_mul_f32_e32 v150, v53, v53
	v_mul_f32_e32 v151, v55, v55
	v_fmac_f32_e32 v150, v52, v52
	v_fmac_f32_e32 v151, v54, v54
	v_add_f32_e32 v150, v150, v151
	v_add_f32_e32 v77, v77, v150
	s_waitcnt vmcnt(4)
	v_mul_f32_e32 v150, v49, v49
	v_mul_f32_e32 v151, v51, v51
	v_fmac_f32_e32 v150, v48, v48
	v_fmac_f32_e32 v151, v50, v50
	v_add_f32_e32 v150, v150, v151
	v_add_f32_e32 v77, v77, v150
	s_waitcnt vmcnt(3)
	v_mul_f32_e32 v150, v45, v45
	v_mul_f32_e32 v151, v47, v47
	v_fmac_f32_e32 v150, v44, v44
	v_fmac_f32_e32 v151, v46, v46
	v_add_f32_e32 v150, v150, v151
	v_add_f32_e32 v77, v77, v150
	s_waitcnt vmcnt(2)
	v_mul_f32_e32 v150, v41, v41
	v_mul_f32_e32 v151, v43, v43
	v_fmac_f32_e32 v150, v40, v40
	v_fmac_f32_e32 v151, v42, v42
	v_add_f32_e32 v150, v150, v151
	v_add_f32_e32 v77, v77, v150
	s_waitcnt vmcnt(1)
; template <int SRC> __device__ __forceinline__ void prenorm_rows(const LArgs& a, int nrows, const float* nw, const float* mods_layer, int shift_part, bf16* dst) {
;     ...
;             for (int j = 0; j < 8; ++j) { v[j] = *(const f32x4*)(src + 4 * lane + 256 * j); ss += (v[j].x * v[j].x + v[j].y * v[j].y) + (v[j].z * v[j].z + v[j].w * v[j].w); }
;             const float rn = 1.f / sqrtf(wave_sum(ss) * (1.f / DM) + 1e-6f);
	v_mul_f32_e32 v150, v37, v37
	v_mul_f32_e32 v151, v39, v39
	v_fmac_f32_e32 v150, v36, v36
	v_fmac_f32_e32 v151, v38, v38
	v_add_f32_e32 v150, v150, v151
	v_add_f32_e32 v77, v77, v150
	s_waitcnt vmcnt(0)
	v_mul_f32_e32 v150, v33, v33
	v_mul_f32_e32 v151, v35, v35
	v_fmac_f32_e32 v150, v32, v32
	v_fmac_f32_e32 v151, v34, v34
	v_add_f32_e32 v150, v150, v151
	v_add_f32_e32 v77, v77, v150
	ds_swizzle_b32 v79, v77 offset:swizzle(SWAP,1)
	s_waitcnt lgkmcnt(0)
	v_add_f32_e32 v77, v77, v79
	ds_swizzle_b32 v79, v77 offset:swizzle(SWAP,2)
	s_waitcnt lgkmcnt(0)
	v_add_f32_e32 v77, v77, v79
	ds_swizzle_b32 v79, v77 offset:swizzle(SWAP,4)
	s_waitcnt lgkmcnt(0)
	v_add_f32_e32 v77, v77, v79
	ds_swizzle_b32 v79, v77 offset:swizzle(SWAP,8)
	s_waitcnt lgkmcnt(0)
	v_add_f32_e32 v77, v77, v79
	ds_swizzle_b32 v79, v77 offset:swizzle(SWAP,16)
	s_waitcnt lgkmcnt(0)
; __device__ __forceinline__ unsigned pk2(float lo, float hi) { return f2bf(lo) | (f2bf(hi) << 16); }
; template <int SRC> __device__ __forceinline__ void prenorm_rows(const LArgs& a, int nrows, const float* nw, const float* mods_layer, int shift_part, bf16* dst) {
;     ...
;     for (int chunk = gw; chunk < nrows / 16; chunk += NGW) {
;     ...
;             const float rn = 1.f / sqrtf(wave_sum(ss) * (1.f / DM) + 1e-6f);
; #pragma unroll
;             for (int j = 0; j < 8; ++j) { const int col = 4 * lane + 256 * j; const f32x4 o = v[j] * rn * cs[j] + sv[j]; u32x2 pq; pq.x = pk2(o.x, o.y); pq.y = pk2(o.z, o.w); *(u32x2*)(dst + (size_t)(row0 + r) * DM + col) = pq; }
;         }
	v_add_f32_e32 v77, v77, v79
	s_nop 0
	v_readlane_b32 s1, v77, 32
	v_readlane_b32 s0, v77, 0
	s_nop 0
	v_mov_b32_e32 v77, s1
	v_add_f32_e32 v77, s0, v77
	v_fmamk_f32 v77, v77, 0x3a000000, v193
	v_cmp_gt_f32_e32 vcc, s61, v77
	v_mul_f32_e32 v79, 0x4f800000, v77
	s_nop 0
	v_cndmask_b32_e32 v77, v77, v79, vcc
	v_sqrt_f32_e32 v79, v77
	s_nop 0
	v_add_u32_e32 v81, -1, v79
	v_fma_f32 v83, -v81, v79, v77
	v_cmp_ge_f32_e64 s[0:1], 0, v83
	v_add_u32_e32 v83, 1, v79
	s_nop 0
	v_cndmask_b32_e64 v81, v79, v81, s[0:1]
	v_fma_f32 v79, -v83, v79, v77
	v_cmp_lt_f32_e64 s[0:1], 0, v79
	s_nop 1
	v_cndmask_b32_e64 v79, v81, v83, s[0:1]
	v_mul_f32_e32 v81, 0x37800000, v79
	v_cndmask_b32_e32 v79, v79, v81, vcc
	v_cmp_class_f32_e32 vcc, v77, v194
	s_nop 1
	v_cndmask_b32_e32 v77, v79, v77, vcc
	v_div_scale_f32 v79, s[0:1], v77, v77, 1.0
	v_rcp_f32_e32 v81, v79
	s_nop 0
	v_fma_f32 v83, -v79, v81, 1.0
	v_fmac_f32_e32 v81, v83, v81
	v_div_scale_f32 v83, vcc, 1.0, v77, 1.0
	v_mul_f32_e32 v85, v83, v81
	v_fma_f32 v87, -v79, v85, v83
	v_fmac_f32_e32 v85, v87, v81
	v_fma_f32 v79, -v79, v85, v83
	v_div_fmas_f32 v79, v79, v81, v85
	v_div_fixup_f32 v126, v79, v77, 1.0
	v_pk_mul_f32 v[60:61], v[60:61], v[126:127] op_sel_hi:[1,0]
	v_pk_mul_f32 v[62:63], v[62:63], v[126:127] op_sel_hi:[1,0]
	v_pk_fma_f32 v[60:61], v[92:93], v[60:61], v[0:1]
	v_pk_fma_f32 v[62:63], v[90:91], v[62:63], v[2:3]
	v_bfe_u32 v77, v60, 16, 1
	v_add3_u32 v60, v60, v77, s72
	v_bfe_u32 v77, v61, 16, 1
	v_lshrrev_b32_e32 v60, 16, v60
	v_add3_u32 v61, v61, v77, s72
	v_and_or_b32 v60, v61, s73, v60
	v_bfe_u32 v61, v62, 16, 1
	v_add3_u32 v61, v62, v61, s72
	v_bfe_u32 v62, v63, 16, 1
	v_lshrrev_b32_e32 v61, 16, v61
	v_add3_u32 v62, v63, v62, s72
	v_pk_mul_f32 v[56:57], v[56:57], v[126:127] op_sel_hi:[1,0]
	v_and_or_b32 v61, v62, s73, v61
	v_lshl_add_u64 v[62:63], v[74:75], 0, v[128:129]
	v_pk_fma_f32 v[56:57], v[96:97], v[56:57], v[4:5]
	global_store_dwordx2 v[62:63], v[60:61], off
	v_bfe_u32 v60, v56, 16, 1
	v_pk_mul_f32 v[58:59], v[58:59], v[126:127] op_sel_hi:[1,0]
	v_add3_u32 v56, v56, v60, s72
	v_bfe_u32 v60, v57, 16, 1
	v_pk_fma_f32 v[58:59], v[94:95], v[58:59], v[6:7]
	v_lshrrev_b32_e32 v56, 16, v56
	v_add3_u32 v57, v57, v60, s72
	v_and_or_b32 v56, v57, s73, v56
	v_bfe_u32 v57, v58, 16, 1
	v_add3_u32 v57, v58, v57, s72
	v_bfe_u32 v58, v59, 16, 1
	v_lshrrev_b32_e32 v57, 16, v57
	v_add3_u32 v58, v59, v58, s72
	v_pk_mul_f32 v[52:53], v[52:53], v[126:127] op_sel_hi:[1,0]
	v_and_or_b32 v57, v58, s73, v57
	v_pk_fma_f32 v[52:53], v[100:101], v[52:53], v[8:9]
	global_store_dwordx2 v[62:63], v[56:57], off offset:512
	v_bfe_u32 v56, v52, 16, 1
	v_pk_mul_f32 v[54:55], v[54:55], v[126:127] op_sel_hi:[1,0]
	v_add3_u32 v52, v52, v56, s72
	v_bfe_u32 v56, v53, 16, 1
	v_pk_fma_f32 v[54:55], v[98:99], v[54:55], v[10:11]
	v_lshrrev_b32_e32 v52, 16, v52
	v_add3_u32 v53, v53, v56, s72
	v_and_or_b32 v52, v53, s73, v52
	v_bfe_u32 v53, v54, 16, 1
	v_add3_u32 v53, v54, v53, s72
	v_bfe_u32 v54, v55, 16, 1
	v_lshrrev_b32_e32 v53, 16, v53
	v_add3_u32 v54, v55, v54, s72
	v_pk_mul_f32 v[48:49], v[48:49], v[126:127] op_sel_hi:[1,0]
	v_and_or_b32 v53, v54, s73, v53
	v_pk_fma_f32 v[48:49], v[104:105], v[48:49], v[12:13]
	global_store_dwordx2 v[62:63], v[52:53], off offset:1024
	v_bfe_u32 v52, v48, 16, 1
	v_pk_mul_f32 v[50:51], v[50:51], v[126:127] op_sel_hi:[1,0]
	v_add3_u32 v48, v48, v52, s72
	v_bfe_u32 v52, v49, 16, 1
	v_pk_fma_f32 v[50:51], v[102:103], v[50:51], v[14:15]
	v_lshrrev_b32_e32 v48, 16, v48
	v_add3_u32 v49, v49, v52, s72
	v_and_or_b32 v48, v49, s73, v48
	v_bfe_u32 v49, v50, 16, 1
	v_add3_u32 v49, v50, v49, s72
	v_bfe_u32 v50, v51, 16, 1
	v_lshrrev_b32_e32 v49, 16, v49
	v_add3_u32 v50, v51, v50, s72
	v_pk_mul_f32 v[44:45], v[44:45], v[126:127] op_sel_hi:[1,0]
	v_and_or_b32 v49, v50, s73, v49
	v_pk_fma_f32 v[44:45], v[108:109], v[44:45], v[16:17]
	global_store_dwordx2 v[62:63], v[48:49], off offset:1536
	v_bfe_u32 v48, v44, 16, 1
	v_pk_mul_f32 v[46:47], v[46:47], v[126:127] op_sel_hi:[1,0]
	v_add3_u32 v44, v44, v48, s72
	v_bfe_u32 v48, v45, 16, 1
	v_pk_fma_f32 v[46:47], v[106:107], v[46:47], v[18:19]
	v_lshrrev_b32_e32 v44, 16, v44
	v_add3_u32 v45, v45, v48, s72
	v_and_or_b32 v44, v45, s73, v44
	v_bfe_u32 v45, v46, 16, 1
	v_add3_u32 v45, v46, v45, s72
	v_bfe_u32 v46, v47, 16, 1
	v_lshrrev_b32_e32 v45, 16, v45
	v_add3_u32 v46, v47, v46, s72
	v_pk_mul_f32 v[40:41], v[40:41], v[126:127] op_sel_hi:[1,0]
	v_and_or_b32 v45, v46, s73, v45
	v_pk_fma_f32 v[40:41], v[112:113], v[40:41], v[20:21]
	global_store_dwordx2 v[62:63], v[44:45], off offset:2048
	v_bfe_u32 v44, v40, 16, 1
	v_pk_mul_f32 v[42:43], v[42:43], v[126:127] op_sel_hi:[1,0]
	v_add3_u32 v40, v40, v44, s72
	v_bfe_u32 v44, v41, 16, 1
	v_pk_fma_f32 v[42:43], v[110:111], v[42:43], v[22:23]
	v_lshrrev_b32_e32 v40, 16, v40
	v_add3_u32 v41, v41, v44, s72
	v_and_or_b32 v40, v41, s73, v40
	v_bfe_u32 v41, v42, 16, 1
	v_add3_u32 v41, v42, v41, s72
	v_bfe_u32 v42, v43, 16, 1
	v_lshrrev_b32_e32 v41, 16, v41
	v_add3_u32 v42, v43, v42, s72
	v_pk_mul_f32 v[36:37], v[36:37], v[126:127] op_sel_hi:[1,0]
	v_and_or_b32 v41, v42, s73, v41
	v_pk_fma_f32 v[36:37], v[116:117], v[36:37], v[24:25]
	global_store_dwordx2 v[62:63], v[40:41], off offset:2560
	v_bfe_u32 v40, v36, 16, 1
	v_pk_mul_f32 v[38:39], v[38:39], v[126:127] op_sel_hi:[1,0]
	v_add3_u32 v36, v36, v40, s72
	v_bfe_u32 v40, v37, 16, 1
	v_pk_fma_f32 v[38:39], v[114:115], v[38:39], v[26:27]
	v_lshrrev_b32_e32 v36, 16, v36
	v_add3_u32 v37, v37, v40, s72
	v_and_or_b32 v36, v37, s73, v36
	v_bfe_u32 v37, v38, 16, 1
	v_add3_u32 v37, v38, v37, s72
	v_bfe_u32 v38, v39, 16, 1
	v_lshrrev_b32_e32 v37, 16, v37
	v_add3_u32 v38, v39, v38, s72
	v_pk_mul_f32 v[32:33], v[32:33], v[126:127] op_sel_hi:[1,0]
	v_and_or_b32 v37, v38, s73, v37
	v_pk_fma_f32 v[32:33], v[120:121], v[32:33], v[28:29]
	global_store_dwordx2 v[62:63], v[36:37], off offset:3072
	v_bfe_u32 v36, v32, 16, 1
	v_pk_mul_f32 v[34:35], v[34:35], v[126:127] op_sel_hi:[1,0]
	v_add3_u32 v32, v32, v36, s72
	v_bfe_u32 v36, v33, 16, 1
	v_pk_fma_f32 v[34:35], v[118:119], v[34:35], v[30:31]
	v_lshrrev_b32_e32 v32, 16, v32
	v_add3_u32 v33, v33, v36, s72
	v_and_or_b32 v32, v33, s73, v32
	v_bfe_u32 v33, v34, 16, 1
	v_add3_u32 v33, v34, v33, s72
	v_bfe_u32 v34, v35, 16, 1
	v_lshrrev_b32_e32 v33, 16, v33
	v_add3_u32 v34, v35, v34, s72
	v_and_or_b32 v33, v34, s73, v33
	global_store_dwordx2 v[62:63], v[32:33], off offset:3584
	s_cbranch_scc0 .LBB0_464
	v_add_u32_e32 v131, s86, v131
	s_movk_i32 s0, 0x81f
	v_cmp_lt_i32_e32 vcc, s0, v131
	v_readlane_b32 s0, v254, 6
	s_or_b64 s[6:7], vcc, s[6:7]
	s_nop 0
	v_add_u32_e32 v132, s0, v132
	s_andn2_b64 exec, exec, s[6:7]
	s_cbranch_execnz .LBB0_459
